# residual epilogues: pool-register copies elided (unpack reads the prefetch registers directly), late prefetch moved after last consumer
# baseline (speedup 1.0000x reference)
; __device__ __forceinline__ u32x4 pack8(f32x4 a, f32x4 b) { u32x4 w; w.x = cvt_pk_bf16(a[0], a[1]); w.y = cvt_pk_bf16(a[2], a[3]); w.z = cvt_pk_bf16(b[0], b[1]); w.w = cvt_pk_bf16(b[2], b[3]); return w; }
;     __device__ __forceinline__ void operator()(const f32x4 (&acc)[2][2][4][2], const Unit& u, int wr, int wc, int fr, int fq) const {
;     ...
;         for (int ai = 0; ai < 2; ++ai)
; #pragma unroll
;             for (int m = 0; m < 4; ++m) {
;                 const int row = row0 + ai * HALF + m * 16; const size_t off = (size_t)row * 2048 + col;
;                 float s = 0.f;
; #pragma unroll
;                 for (int bj = 0; bj < 2; ++bj) {
;                     f32x4 b0, b1;
;                     if (BASE_F32) { const float* bp = (const float*)base + off + bj * 32; b0 = *(const f32x4*)bp; b1 = *(const f32x4*)(bp + 4); }
;                     else { const u32x4 w = *(const u32x4*)((const bf16_t*)base + off + bj * 32);
;                         b0 = (f32x4){__uint_as_float(w.x << 16), __uint_as_float(w.x & 0xffff0000u), __uint_as_float(w.y << 16), __uint_as_float(w.y & 0xffff0000u)};
;                         b1 = (f32x4){__uint_as_float(w.z << 16), __uint_as_float(w.z & 0xffff0000u), __uint_as_float(w.w << 16), __uint_as_float(w.w & 0xffff0000u)}; }
;                     const f32x4 h0 = b0 + acc[ai][bj][m][0], h1 = b1 + acc[ai][bj][m][1];
;                     s += (h0[0] * h0[0] + h0[1] * h0[1]) + (h0[2] * h0[2] + h0[3] * h0[3]) + (h1[0] * h1[0] + h1[1] * h1[1]) + (h1[2] * h1[2] + h1[3] * h1[3]);
;                     *(u32x4*)(H + off + bj * 32) = pack8(h0, h1);
;                 }
;                 s += __shfl_xor(s, 16); s += __shfl_xor(s, 32);
;                 if (fq == 0) __hip_atomic_fetch_add(ss + row, s, __ATOMIC_RELAXED, __HIP_MEMORY_SCOPE_AGENT);
;                 if (m & 1) asm volatile("" ::: "memory");
;             }
.LBB0_331:
	v_lshl_add_u32 v136, s22, 8, v138
	v_ashrrev_i32_e32 v137, 31, v136
	v_lshl_or_b32 v134, s24, 8, v140
	v_lshlrev_b64 v[142:143], 12, v[136:137]
	v_ashrrev_i32_e32 v135, 31, v134
	v_lshl_add_u64 v[142:143], s[6:7], 0, v[142:143]
	v_lshl_add_u64 v[146:147], v[134:135], 1, v[142:143]
	v_mov_b32_e32 v168, v136
	v_ashrrev_i32_e32 v169, 31, v168
	v_lshlrev_b64 v[168:169], 12, v[168:169]
	v_lshl_add_u64 v[168:169], s[6:7], 0, v[168:169]
	v_lshl_add_u64 v[168:169], v[134:135], 1, v[168:169]
	global_load_dwordx4 v[152:155], v[168:169], off
	global_load_dwordx4 v[156:159], v[168:169], off offset:64
	v_add_u32_e32 v168, 0x10, v136
	v_ashrrev_i32_e32 v169, 31, v168
	v_lshlrev_b64 v[168:169], 12, v[168:169]
	v_lshl_add_u64 v[168:169], s[6:7], 0, v[168:169]
	v_lshl_add_u64 v[168:169], v[134:135], 1, v[168:169]
	global_load_dwordx4 v[160:163], v[168:169], off
	global_load_dwordx4 v[164:167], v[168:169], off offset:64
	v_add_u32_e32 v168, 0x20, v136
	v_ashrrev_i32_e32 v169, 31, v168
	v_lshlrev_b64 v[168:169], 12, v[168:169]
	v_lshl_add_u64 v[168:169], s[6:7], 0, v[168:169]
	v_lshl_add_u64 v[168:169], v[134:135], 1, v[168:169]
	global_load_dwordx4 v[178:181], v[168:169], off
	global_load_dwordx4 v[182:185], v[168:169], off offset:64
	v_add_u32_e32 v168, 0x30, v136
	v_ashrrev_i32_e32 v169, 31, v168
	v_lshlrev_b64 v[168:169], 12, v[168:169]
	v_lshl_add_u64 v[168:169], s[6:7], 0, v[168:169]
	v_lshl_add_u64 v[168:169], v[134:135], 1, v[168:169]
	global_load_dwordx4 v[186:189], v[168:169], off
	global_load_dwordx4 v[190:193], v[168:169], off offset:64
	v_add_u32_e32 v168, 0x80, v136
	v_ashrrev_i32_e32 v169, 31, v168
	v_lshlrev_b64 v[168:169], 12, v[168:169]
	v_lshl_add_u64 v[168:169], s[6:7], 0, v[168:169]
	v_lshl_add_u64 v[168:169], v[134:135], 1, v[168:169]
	global_load_dwordx4 v[194:197], v[168:169], off
	global_load_dwordx4 v[198:201], v[168:169], off offset:64
	v_add_u32_e32 v168, 0x90, v136
	v_ashrrev_i32_e32 v169, 31, v168
	v_lshlrev_b64 v[168:169], 12, v[168:169]
	v_lshl_add_u64 v[168:169], s[6:7], 0, v[168:169]
	v_lshl_add_u64 v[168:169], v[134:135], 1, v[168:169]
	global_load_dwordx4 v[212:215], v[168:169], off
	global_load_dwordx4 v[216:219], v[168:169], off offset:64
	s_nop 1
	s_waitcnt vmcnt(11)
	s_nop 0
	v_lshlrev_b32_e32 v148, 16, v152
	v_and_b32_e32 v149, 0xffff0000, v152
	v_lshlrev_b32_e32 v142, 16, v153
	v_and_b32_e32 v143, 0xffff0000, v153
	v_lshlrev_b32_e32 v150, 16, v154
	v_and_b32_e32 v151, 0xffff0000, v154
	v_lshlrev_b32_e32 v144, 16, v155
	v_and_b32_e32 v145, 0xffff0000, v155
	v_pk_add_f32 v[126:127], v[126:127], v[142:143]
	v_pk_add_f32 v[124:125], v[124:125], v[148:149]
	v_pk_add_f32 v[142:143], v[122:123], v[144:145]
	v_pk_add_f32 v[122:123], v[120:121], v[150:151]
	v_mul_f32_e32 v120, v125, v125
	v_mul_f32_e32 v121, v127, v127
	v_fmac_f32_e32 v120, v124, v124
	v_fmac_f32_e32 v121, v126, v126
	v_add_f32_e32 v120, v120, v121
	v_mul_f32_e32 v121, v123, v123
	v_fmac_f32_e32 v121, v122, v122
	v_add_f32_e32 v120, v121, v120
	v_mul_f32_e32 v121, v143, v143
	v_fmac_f32_e32 v121, v142, v142
	v_add_f32_e32 v144, v121, v120
	v_cvt_pk_bf16_f32 v120, v124, v125
	v_cvt_pk_bf16_f32 v121, v126, v127
	v_cvt_pk_bf16_f32 v122, v122, v123
	v_cvt_pk_bf16_f32 v123, v142, v143
	global_store_dwordx4 v[146:147], v[120:123], off
	s_nop 1
	s_waitcnt vmcnt(11)
	s_nop 0
	v_lshlrev_b32_e32 v124, 16, v156
	v_and_b32_e32 v125, 0xffff0000, v156
	v_lshlrev_b32_e32 v120, 16, v157
	v_and_b32_e32 v121, 0xffff0000, v157
	v_lshlrev_b32_e32 v126, 16, v158
	v_and_b32_e32 v127, 0xffff0000, v158
	v_lshlrev_b32_e32 v122, 16, v159
	v_and_b32_e32 v123, 0xffff0000, v159
	v_add_u32_e32 v168, 0xa0, v136
	v_ashrrev_i32_e32 v169, 31, v168
	v_lshlrev_b64 v[168:169], 12, v[168:169]
	v_lshl_add_u64 v[168:169], s[6:7], 0, v[168:169]
	v_lshl_add_u64 v[168:169], v[134:135], 1, v[168:169]
	global_load_dwordx4 v[152:155], v[168:169], off
	global_load_dwordx4 v[156:159], v[168:169], off offset:64
	v_pk_add_f32 v[118:119], v[118:119], v[120:121]
	v_pk_add_f32 v[116:117], v[116:117], v[124:125]
	v_pk_add_f32 v[120:121], v[114:115], v[122:123]
	v_pk_add_f32 v[114:115], v[112:113], v[126:127]
	v_mul_f32_e32 v112, v117, v117
	v_mul_f32_e32 v113, v119, v119
	v_fmac_f32_e32 v112, v116, v116
	v_fmac_f32_e32 v113, v118, v118
	v_add_f32_e32 v112, v112, v113
	v_mul_f32_e32 v113, v115, v115
	v_fmac_f32_e32 v113, v114, v114
	v_add_f32_e32 v112, v113, v112
	v_mul_f32_e32 v113, v121, v121
	v_fmac_f32_e32 v113, v120, v120
	v_add_f32_e32 v112, v113, v112
	v_add_f32_e32 v122, v144, v112
	v_cvt_pk_bf16_f32 v112, v116, v117
	v_cvt_pk_bf16_f32 v113, v118, v119
	v_cvt_pk_bf16_f32 v114, v114, v115
	v_cvt_pk_bf16_f32 v115, v120, v121
	global_store_dwordx4 v[146:147], v[112:115], off offset:64
	s_nop 1
	v_and_b32_e32 v113, 64, v209
	v_xor_b32_e32 v112, 16, v209
	v_add_u32_e32 v113, 64, v113
	v_cmp_lt_i32_e32 vcc, v112, v113
	v_xor_b32_e32 v115, 32, v209
	s_nop 0
	v_cndmask_b32_e32 v112, v209, v112, vcc
	v_lshlrev_b32_e32 v114, 2, v112
	ds_bpermute_b32 v112, v114, v122
	v_cmp_lt_i32_e32 vcc, v115, v113
	s_waitcnt lgkmcnt(0)
	v_add_f32_e32 v112, v122, v112
	v_cndmask_b32_e32 v113, v209, v115, vcc
	v_lshlrev_b32_e32 v115, 2, v113
	ds_bpermute_b32 v113, v115, v112
	s_and_saveexec_b64 s[22:23], s[2:3]
	s_cbranch_execz .LBB0_333
	v_lshl_add_u64 v[116:117], v[136:137], 2, s[8:9]
	s_waitcnt lgkmcnt(0)
	v_add_f32_e32 v112, v112, v113
	global_atomic_add_f32 v[116:117], v112, off
; __device__ __forceinline__ u32x4 pack8(f32x4 a, f32x4 b) { u32x4 w; w.x = cvt_pk_bf16(a[0], a[1]); w.y = cvt_pk_bf16(a[2], a[3]); w.z = cvt_pk_bf16(b[0], b[1]); w.w = cvt_pk_bf16(b[2], b[3]); return w; }
;     __device__ __forceinline__ void operator()(const f32x4 (&acc)[2][2][4][2], const Unit& u, int wr, int wc, int fr, int fq) const {
;     ...
;         for (int ai = 0; ai < 2; ++ai)
; #pragma unroll
;             for (int m = 0; m < 4; ++m) {
;                 const int row = row0 + ai * HALF + m * 16; const size_t off = (size_t)row * 2048 + col;
;                 float s = 0.f;
; #pragma unroll
;                 for (int bj = 0; bj < 2; ++bj) {
;                     f32x4 b0, b1;
;                     if (BASE_F32) { const float* bp = (const float*)base + off + bj * 32; b0 = *(const f32x4*)bp; b1 = *(const f32x4*)(bp + 4); }
;                     else { const u32x4 w = *(const u32x4*)((const bf16_t*)base + off + bj * 32);
;                         b0 = (f32x4){__uint_as_float(w.x << 16), __uint_as_float(w.x & 0xffff0000u), __uint_as_float(w.y << 16), __uint_as_float(w.y & 0xffff0000u)};
;                         b1 = (f32x4){__uint_as_float(w.z << 16), __uint_as_float(w.z & 0xffff0000u), __uint_as_float(w.w << 16), __uint_as_float(w.w & 0xffff0000u)}; }
;                     const f32x4 h0 = b0 + acc[ai][bj][m][0], h1 = b1 + acc[ai][bj][m][1];
;                     s += (h0[0] * h0[0] + h0[1] * h0[1]) + (h0[2] * h0[2] + h0[3] * h0[3]) + (h1[0] * h1[0] + h1[1] * h1[1]) + (h1[2] * h1[2] + h1[3] * h1[3]);
;                     *(u32x4*)(H + off + bj * 32) = pack8(h0, h1);
;                 }
;                 s += __shfl_xor(s, 16); s += __shfl_xor(s, 32);
;                 if (fq == 0) __hip_atomic_fetch_add(ss + row, s, __ATOMIC_RELAXED, __HIP_MEMORY_SCOPE_AGENT);
;                 if (m & 1) asm volatile("" ::: "memory");
;             }
.LBB0_333:
	s_or_b64 exec, exec, s[22:23]
	v_or_b32_e32 v112, 16, v136
	s_waitcnt lgkmcnt(0)
	v_ashrrev_i32_e32 v113, 31, v112
	v_lshlrev_b64 v[116:117], 12, v[112:113]
	v_lshl_add_u64 v[116:117], s[6:7], 0, v[116:117]
	v_lshl_add_u64 v[120:121], v[134:135], 1, v[116:117]
	s_nop 1
	s_waitcnt vmcnt(13)
	s_nop 0
	v_lshlrev_b32_e32 v122, 16, v160
	v_and_b32_e32 v123, 0xffff0000, v160
	v_lshlrev_b32_e32 v116, 16, v161
	v_and_b32_e32 v117, 0xffff0000, v161
	v_lshlrev_b32_e32 v124, 16, v162
	v_and_b32_e32 v125, 0xffff0000, v162
	v_lshlrev_b32_e32 v118, 16, v163
	v_and_b32_e32 v119, 0xffff0000, v163
	v_pk_add_f32 v[116:117], v[110:111], v[116:117]
	v_pk_add_f32 v[122:123], v[108:109], v[122:123]
	v_pk_add_f32 v[118:119], v[106:107], v[118:119]
	v_pk_add_f32 v[124:125], v[104:105], v[124:125]
	v_cvt_pk_bf16_f32 v104, v122, v123
	v_cvt_pk_bf16_f32 v105, v116, v117
	v_mul_f32_e32 v123, v123, v123
	v_cvt_pk_bf16_f32 v106, v124, v125
	v_cvt_pk_bf16_f32 v107, v118, v119
	s_nop 1
	s_waitcnt vmcnt(12)
	v_mul_f32_e32 v117, v117, v117
	v_mul_f32_e32 v125, v125, v125
	v_fmac_f32_e32 v123, v122, v122
	v_fmac_f32_e32 v117, v116, v116
	v_mul_f32_e32 v119, v119, v119
	v_fmac_f32_e32 v125, v124, v124
	v_add_f32_e32 v116, v123, v117
	v_fmac_f32_e32 v119, v118, v118
	v_add_f32_e32 v116, v125, v116
	v_add_f32_e32 v122, v119, v116
	global_store_dwordx4 v[120:121], v[104:107], off
	s_nop 0
	v_lshlrev_b32_e32 v116, 16, v164
	v_and_b32_e32 v117, 0xffff0000, v164
	v_lshlrev_b32_e32 v108, 16, v165
	v_and_b32_e32 v109, 0xffff0000, v165
	v_lshlrev_b32_e32 v118, 16, v166
	v_and_b32_e32 v119, 0xffff0000, v166
	v_lshlrev_b32_e32 v110, 16, v167
	v_and_b32_e32 v111, 0xffff0000, v167
	v_add_u32_e32 v168, 0xb0, v136
	v_ashrrev_i32_e32 v169, 31, v168
	v_lshlrev_b64 v[168:169], 12, v[168:169]
	v_lshl_add_u64 v[168:169], s[6:7], 0, v[168:169]
	v_lshl_add_u64 v[168:169], v[134:135], 1, v[168:169]
	global_load_dwordx4 v[160:163], v[168:169], off
	global_load_dwordx4 v[164:167], v[168:169], off offset:64
	v_pk_add_f32 v[102:103], v[102:103], v[108:109]
	v_pk_add_f32 v[100:101], v[100:101], v[116:117]
	v_pk_add_f32 v[108:109], v[98:99], v[110:111]
	v_pk_add_f32 v[110:111], v[96:97], v[118:119]
	v_mul_f32_e32 v96, v101, v101
	v_mul_f32_e32 v97, v103, v103
	v_mul_f32_e32 v98, v111, v111
	v_fmac_f32_e32 v96, v100, v100
	v_fmac_f32_e32 v97, v102, v102
	v_mul_f32_e32 v99, v109, v109
	v_fmac_f32_e32 v98, v110, v110
	v_add_f32_e32 v96, v96, v97
	v_add_f32_e32 v96, v98, v96
	v_fmac_f32_e32 v99, v108, v108
	v_add_f32_e32 v96, v99, v96
	v_add_f32_e32 v96, v122, v96
	ds_bpermute_b32 v97, v114, v96
	v_cvt_pk_bf16_f32 v98, v100, v101
	v_cvt_pk_bf16_f32 v99, v102, v103
	v_cvt_pk_bf16_f32 v100, v110, v111
	v_cvt_pk_bf16_f32 v101, v108, v109
	s_waitcnt lgkmcnt(0)
	v_add_f32_e32 v96, v96, v97
	ds_bpermute_b32 v97, v115, v96
	global_store_dwordx4 v[120:121], v[98:101], off offset:64
	s_and_saveexec_b64 s[22:23], s[2:3]
	s_cbranch_execz .LBB0_335
	v_lshl_add_u64 v[98:99], v[112:113], 2, s[8:9]
	s_waitcnt lgkmcnt(0)
	v_add_f32_e32 v96, v96, v97
	global_atomic_add_f32 v[98:99], v96, off
.LBB0_335:
	s_or_b64 exec, exec, s[22:23]
	v_or_b32_e32 v96, 32, v136
	s_waitcnt lgkmcnt(0)
	v_ashrrev_i32_e32 v97, 31, v96
	v_lshlrev_b64 v[98:99], 12, v[96:97]
	v_lshl_add_u64 v[98:99], s[6:7], 0, v[98:99]
	v_lshl_add_u64 v[102:103], v[134:135], 1, v[98:99]
	s_nop 1
	s_waitcnt vmcnt(15)
	s_nop 0
	v_lshlrev_b32_e32 v104, 16, v178
	v_and_b32_e32 v105, 0xffff0000, v178
	v_lshlrev_b32_e32 v98, 16, v179
	v_and_b32_e32 v99, 0xffff0000, v179
	v_lshlrev_b32_e32 v106, 16, v180
	v_and_b32_e32 v107, 0xffff0000, v180
	v_lshlrev_b32_e32 v100, 16, v181
	v_and_b32_e32 v101, 0xffff0000, v181
	v_pk_add_f32 v[98:99], v[94:95], v[98:99]
	v_pk_add_f32 v[104:105], v[92:93], v[104:105]
	v_pk_add_f32 v[100:101], v[90:91], v[100:101]
	v_pk_add_f32 v[106:107], v[88:89], v[106:107]
	v_cvt_pk_bf16_f32 v88, v104, v105
	v_cvt_pk_bf16_f32 v89, v98, v99
	v_mul_f32_e32 v105, v105, v105
	v_cvt_pk_bf16_f32 v90, v106, v107
	v_cvt_pk_bf16_f32 v91, v100, v101
	s_nop 1
	s_waitcnt vmcnt(14)
	v_mul_f32_e32 v99, v99, v99
	v_mul_f32_e32 v107, v107, v107
	v_fmac_f32_e32 v105, v104, v104
	v_fmac_f32_e32 v99, v98, v98
	v_mul_f32_e32 v101, v101, v101
	v_fmac_f32_e32 v107, v106, v106
	v_add_f32_e32 v98, v105, v99
	v_fmac_f32_e32 v101, v100, v100
	v_add_f32_e32 v98, v107, v98
	v_add_f32_e32 v104, v101, v98
	global_store_dwordx4 v[102:103], v[88:91], off
	s_nop 0
	v_lshlrev_b32_e32 v98, 16, v182
	v_and_b32_e32 v99, 0xffff0000, v182
	v_lshlrev_b32_e32 v92, 16, v183
	v_and_b32_e32 v93, 0xffff0000, v183
	v_lshlrev_b32_e32 v100, 16, v184
	v_and_b32_e32 v101, 0xffff0000, v184
	v_lshlrev_b32_e32 v94, 16, v185
	v_and_b32_e32 v95, 0xffff0000, v185
	v_pk_add_f32 v[86:87], v[86:87], v[92:93]
	v_pk_add_f32 v[84:85], v[84:85], v[98:99]
	v_pk_add_f32 v[92:93], v[82:83], v[94:95]
	v_pk_add_f32 v[94:95], v[80:81], v[100:101]
	v_mul_f32_e32 v80, v85, v85
	v_mul_f32_e32 v81, v87, v87
	v_mul_f32_e32 v82, v95, v95
	v_fmac_f32_e32 v80, v84, v84
	v_fmac_f32_e32 v81, v86, v86
	v_mul_f32_e32 v83, v93, v93
	v_fmac_f32_e32 v82, v94, v94
	v_add_f32_e32 v80, v80, v81
	v_add_f32_e32 v80, v82, v80
	v_fmac_f32_e32 v83, v92, v92
	v_add_f32_e32 v80, v83, v80
	v_add_f32_e32 v80, v104, v80
	ds_bpermute_b32 v81, v114, v80
	v_cvt_pk_bf16_f32 v82, v84, v85
	v_cvt_pk_bf16_f32 v83, v86, v87
	v_cvt_pk_bf16_f32 v84, v94, v95
	v_cvt_pk_bf16_f32 v85, v92, v93
	s_waitcnt lgkmcnt(0)
	v_add_f32_e32 v80, v80, v81
	ds_bpermute_b32 v81, v115, v80
	global_store_dwordx4 v[102:103], v[82:85], off offset:64
	s_and_saveexec_b64 s[22:23], s[2:3]
	s_cbranch_execz .LBB0_337
	v_lshl_add_u64 v[82:83], v[96:97], 2, s[8:9]
	s_waitcnt lgkmcnt(0)
	v_add_f32_e32 v80, v80, v81
	global_atomic_add_f32 v[82:83], v80, off
; __device__ __forceinline__ u32x4 pack8(f32x4 a, f32x4 b) { u32x4 w; w.x = cvt_pk_bf16(a[0], a[1]); w.y = cvt_pk_bf16(a[2], a[3]); w.z = cvt_pk_bf16(b[0], b[1]); w.w = cvt_pk_bf16(b[2], b[3]); return w; }
;     __device__ __forceinline__ void operator()(const f32x4 (&acc)[2][2][4][2], const Unit& u, int wr, int wc, int fr, int fq) const {
;     ...
;         for (int ai = 0; ai < 2; ++ai)
; #pragma unroll
;             for (int m = 0; m < 4; ++m) {
;                 const int row = row0 + ai * HALF + m * 16; const size_t off = (size_t)row * 2048 + col;
;                 float s = 0.f;
; #pragma unroll
;                 for (int bj = 0; bj < 2; ++bj) {
;                     f32x4 b0, b1;
;                     if (BASE_F32) { const float* bp = (const float*)base + off + bj * 32; b0 = *(const f32x4*)bp; b1 = *(const f32x4*)(bp + 4); }
;                     else { const u32x4 w = *(const u32x4*)((const bf16_t*)base + off + bj * 32);
;                         b0 = (f32x4){__uint_as_float(w.x << 16), __uint_as_float(w.x & 0xffff0000u), __uint_as_float(w.y << 16), __uint_as_float(w.y & 0xffff0000u)};
;                         b1 = (f32x4){__uint_as_float(w.z << 16), __uint_as_float(w.z & 0xffff0000u), __uint_as_float(w.w << 16), __uint_as_float(w.w & 0xffff0000u)}; }
;                     const f32x4 h0 = b0 + acc[ai][bj][m][0], h1 = b1 + acc[ai][bj][m][1];
;                     s += (h0[0] * h0[0] + h0[1] * h0[1]) + (h0[2] * h0[2] + h0[3] * h0[3]) + (h1[0] * h1[0] + h1[1] * h1[1]) + (h1[2] * h1[2] + h1[3] * h1[3]);
;                     *(u32x4*)(H + off + bj * 32) = pack8(h0, h1);
;                 }
;                 s += __shfl_xor(s, 16); s += __shfl_xor(s, 32);
;                 if (fq == 0) __hip_atomic_fetch_add(ss + row, s, __ATOMIC_RELAXED, __HIP_MEMORY_SCOPE_AGENT);
;                 if (m & 1) asm volatile("" ::: "memory");
;             }
.LBB0_337:
	s_or_b64 exec, exec, s[22:23]
	v_or_b32_e32 v80, 48, v136
	s_waitcnt lgkmcnt(0)
	v_ashrrev_i32_e32 v81, 31, v80
	v_lshlrev_b64 v[82:83], 12, v[80:81]
	v_lshl_add_u64 v[82:83], s[6:7], 0, v[82:83]
	v_lshl_add_u64 v[86:87], v[134:135], 1, v[82:83]
	s_nop 1
	s_waitcnt vmcnt(15)
	s_nop 0
	v_lshlrev_b32_e32 v88, 16, v186
	v_and_b32_e32 v89, 0xffff0000, v186
	v_lshlrev_b32_e32 v82, 16, v187
	v_and_b32_e32 v83, 0xffff0000, v187
	v_lshlrev_b32_e32 v90, 16, v188
	v_and_b32_e32 v91, 0xffff0000, v188
	v_lshlrev_b32_e32 v84, 16, v189
	v_and_b32_e32 v85, 0xffff0000, v189
	v_pk_add_f32 v[82:83], v[78:79], v[82:83]
	v_pk_add_f32 v[88:89], v[76:77], v[88:89]
	v_pk_add_f32 v[84:85], v[74:75], v[84:85]
	v_pk_add_f32 v[90:91], v[72:73], v[90:91]
	v_cvt_pk_bf16_f32 v72, v88, v89
	v_cvt_pk_bf16_f32 v73, v82, v83
	v_mul_f32_e32 v89, v89, v89
	v_cvt_pk_bf16_f32 v74, v90, v91
	v_cvt_pk_bf16_f32 v75, v84, v85
	s_nop 1
	s_waitcnt vmcnt(14)
	v_mul_f32_e32 v83, v83, v83
	v_mul_f32_e32 v91, v91, v91
	v_fmac_f32_e32 v89, v88, v88
	v_fmac_f32_e32 v83, v82, v82
	v_mul_f32_e32 v85, v85, v85
	v_fmac_f32_e32 v91, v90, v90
	v_add_f32_e32 v82, v89, v83
	v_fmac_f32_e32 v85, v84, v84
	v_add_f32_e32 v82, v91, v82
	v_add_f32_e32 v88, v85, v82
	global_store_dwordx4 v[86:87], v[72:75], off
	s_nop 0
	v_lshlrev_b32_e32 v82, 16, v190
	v_and_b32_e32 v83, 0xffff0000, v190
	v_lshlrev_b32_e32 v76, 16, v191
	v_and_b32_e32 v77, 0xffff0000, v191
	v_lshlrev_b32_e32 v84, 16, v192
	v_and_b32_e32 v85, 0xffff0000, v192
	v_lshlrev_b32_e32 v78, 16, v193
	v_and_b32_e32 v79, 0xffff0000, v193
	v_pk_add_f32 v[70:71], v[70:71], v[76:77]
	v_pk_add_f32 v[68:69], v[68:69], v[82:83]
	v_pk_add_f32 v[76:77], v[66:67], v[78:79]
	v_pk_add_f32 v[78:79], v[64:65], v[84:85]
	v_mul_f32_e32 v64, v69, v69
	v_mul_f32_e32 v65, v71, v71
	v_mul_f32_e32 v66, v79, v79
	v_fmac_f32_e32 v64, v68, v68
	v_fmac_f32_e32 v65, v70, v70
	v_mul_f32_e32 v67, v77, v77
	v_fmac_f32_e32 v66, v78, v78
	v_add_f32_e32 v64, v64, v65
	v_add_f32_e32 v64, v66, v64
	v_fmac_f32_e32 v67, v76, v76
	v_add_f32_e32 v64, v67, v64
	v_add_f32_e32 v64, v88, v64
	ds_bpermute_b32 v65, v114, v64
	v_cvt_pk_bf16_f32 v66, v68, v69
	v_cvt_pk_bf16_f32 v67, v70, v71
	v_cvt_pk_bf16_f32 v68, v78, v79
	v_cvt_pk_bf16_f32 v69, v76, v77
	s_waitcnt lgkmcnt(0)
	v_add_f32_e32 v64, v64, v65
	ds_bpermute_b32 v65, v115, v64
	global_store_dwordx4 v[86:87], v[66:69], off offset:64
	s_and_saveexec_b64 s[22:23], s[2:3]
	s_cbranch_execz .LBB0_339
	v_lshl_add_u64 v[66:67], v[80:81], 2, s[8:9]
	s_waitcnt lgkmcnt(0)
	v_add_f32_e32 v64, v64, v65
	global_atomic_add_f32 v[66:67], v64, off
.LBB0_339:
	s_or_b64 exec, exec, s[22:23]
	v_add_u32_e32 v64, 0x80, v136
	s_waitcnt lgkmcnt(0)
	v_ashrrev_i32_e32 v65, 31, v64
	v_lshlrev_b64 v[66:67], 12, v[64:65]
	v_lshl_add_u64 v[66:67], s[6:7], 0, v[66:67]
	v_lshl_add_u64 v[70:71], v[134:135], 1, v[66:67]
	s_nop 1
	s_waitcnt vmcnt(15)
	s_nop 0
	v_lshlrev_b32_e32 v72, 16, v194
	v_and_b32_e32 v73, 0xffff0000, v194
	v_lshlrev_b32_e32 v66, 16, v195
	v_and_b32_e32 v67, 0xffff0000, v195
	v_lshlrev_b32_e32 v74, 16, v196
	v_and_b32_e32 v75, 0xffff0000, v196
	v_lshlrev_b32_e32 v68, 16, v197
	v_and_b32_e32 v69, 0xffff0000, v197
	v_pk_add_f32 v[66:67], v[62:63], v[66:67]
	v_pk_add_f32 v[72:73], v[60:61], v[72:73]
	v_pk_add_f32 v[68:69], v[58:59], v[68:69]
	v_pk_add_f32 v[74:75], v[56:57], v[74:75]
	v_cvt_pk_bf16_f32 v56, v72, v73
	v_cvt_pk_bf16_f32 v57, v66, v67
	v_mul_f32_e32 v73, v73, v73
	v_cvt_pk_bf16_f32 v58, v74, v75
	v_cvt_pk_bf16_f32 v59, v68, v69
	s_nop 1
	s_waitcnt vmcnt(14)
	v_mul_f32_e32 v67, v67, v67
	v_mul_f32_e32 v75, v75, v75
	v_fmac_f32_e32 v73, v72, v72
	v_fmac_f32_e32 v67, v66, v66
	v_mul_f32_e32 v69, v69, v69
	v_fmac_f32_e32 v75, v74, v74
	v_add_f32_e32 v66, v73, v67
	v_fmac_f32_e32 v69, v68, v68
	v_add_f32_e32 v66, v75, v66
	v_add_f32_e32 v72, v69, v66
	global_store_dwordx4 v[70:71], v[56:59], off
	s_nop 0
	v_lshlrev_b32_e32 v66, 16, v198
	v_and_b32_e32 v67, 0xffff0000, v198
	v_lshlrev_b32_e32 v60, 16, v199
	v_and_b32_e32 v61, 0xffff0000, v199
	v_lshlrev_b32_e32 v68, 16, v200
	v_and_b32_e32 v69, 0xffff0000, v200
	v_lshlrev_b32_e32 v62, 16, v201
	v_and_b32_e32 v63, 0xffff0000, v201
	v_pk_add_f32 v[54:55], v[54:55], v[60:61]
	v_pk_add_f32 v[52:53], v[52:53], v[66:67]
	v_pk_add_f32 v[60:61], v[50:51], v[62:63]
	v_pk_add_f32 v[62:63], v[48:49], v[68:69]
	v_mul_f32_e32 v48, v53, v53
	v_mul_f32_e32 v49, v55, v55
	v_mul_f32_e32 v50, v63, v63
	v_fmac_f32_e32 v48, v52, v52
	v_fmac_f32_e32 v49, v54, v54
	v_mul_f32_e32 v51, v61, v61
	v_fmac_f32_e32 v50, v62, v62
	v_add_f32_e32 v48, v48, v49
	v_add_f32_e32 v48, v50, v48
	v_fmac_f32_e32 v51, v60, v60
	v_add_f32_e32 v48, v51, v48
	v_add_f32_e32 v48, v72, v48
	ds_bpermute_b32 v49, v114, v48
	v_cvt_pk_bf16_f32 v50, v52, v53
	v_cvt_pk_bf16_f32 v51, v54, v55
	v_cvt_pk_bf16_f32 v52, v62, v63
	v_cvt_pk_bf16_f32 v53, v60, v61
	s_waitcnt lgkmcnt(0)
	v_add_f32_e32 v48, v48, v49
	ds_bpermute_b32 v49, v115, v48
	global_store_dwordx4 v[70:71], v[50:53], off offset:64
	s_and_saveexec_b64 s[22:23], s[2:3]
	s_cbranch_execz .LBB0_341
	v_lshl_add_u64 v[50:51], v[64:65], 2, s[8:9]
	s_waitcnt lgkmcnt(0)
	v_add_f32_e32 v48, v48, v49
	global_atomic_add_f32 v[50:51], v48, off
; __device__ __forceinline__ u32x4 pack8(f32x4 a, f32x4 b) { u32x4 w; w.x = cvt_pk_bf16(a[0], a[1]); w.y = cvt_pk_bf16(a[2], a[3]); w.z = cvt_pk_bf16(b[0], b[1]); w.w = cvt_pk_bf16(b[2], b[3]); return w; }
;     __device__ __forceinline__ void operator()(const f32x4 (&acc)[2][2][4][2], const Unit& u, int wr, int wc, int fr, int fq) const {
;     ...
;         for (int ai = 0; ai < 2; ++ai)
; #pragma unroll
;             for (int m = 0; m < 4; ++m) {
;                 const int row = row0 + ai * HALF + m * 16; const size_t off = (size_t)row * 2048 + col;
;                 float s = 0.f;
; #pragma unroll
;                 for (int bj = 0; bj < 2; ++bj) {
;                     f32x4 b0, b1;
;                     if (BASE_F32) { const float* bp = (const float*)base + off + bj * 32; b0 = *(const f32x4*)bp; b1 = *(const f32x4*)(bp + 4); }
;                     else { const u32x4 w = *(const u32x4*)((const bf16_t*)base + off + bj * 32);
;                         b0 = (f32x4){__uint_as_float(w.x << 16), __uint_as_float(w.x & 0xffff0000u), __uint_as_float(w.y << 16), __uint_as_float(w.y & 0xffff0000u)};
;                         b1 = (f32x4){__uint_as_float(w.z << 16), __uint_as_float(w.z & 0xffff0000u), __uint_as_float(w.w << 16), __uint_as_float(w.w & 0xffff0000u)}; }
;                     const f32x4 h0 = b0 + acc[ai][bj][m][0], h1 = b1 + acc[ai][bj][m][1];
;                     s += (h0[0] * h0[0] + h0[1] * h0[1]) + (h0[2] * h0[2] + h0[3] * h0[3]) + (h1[0] * h1[0] + h1[1] * h1[1]) + (h1[2] * h1[2] + h1[3] * h1[3]);
;                     *(u32x4*)(H + off + bj * 32) = pack8(h0, h1);
;                 }
;                 s += __shfl_xor(s, 16); s += __shfl_xor(s, 32);
;                 if (fq == 0) __hip_atomic_fetch_add(ss + row, s, __ATOMIC_RELAXED, __HIP_MEMORY_SCOPE_AGENT);
;                 if (m & 1) asm volatile("" ::: "memory");
;             }
.LBB0_341:
	s_or_b64 exec, exec, s[22:23]
	v_add_u32_e32 v48, 0x90, v136
	s_waitcnt lgkmcnt(0)
	v_ashrrev_i32_e32 v49, 31, v48
	v_lshlrev_b64 v[50:51], 12, v[48:49]
	v_lshl_add_u64 v[50:51], s[6:7], 0, v[50:51]
	v_lshl_add_u64 v[54:55], v[134:135], 1, v[50:51]
	s_nop 1
	s_waitcnt vmcnt(15)
	s_nop 0
	v_lshlrev_b32_e32 v56, 16, v212
	v_and_b32_e32 v57, 0xffff0000, v212
	v_lshlrev_b32_e32 v50, 16, v213
	v_and_b32_e32 v51, 0xffff0000, v213
	v_lshlrev_b32_e32 v58, 16, v214
	v_and_b32_e32 v59, 0xffff0000, v214
	v_lshlrev_b32_e32 v52, 16, v215
	v_and_b32_e32 v53, 0xffff0000, v215
	v_pk_add_f32 v[50:51], v[46:47], v[50:51]
	v_pk_add_f32 v[56:57], v[44:45], v[56:57]
	v_pk_add_f32 v[52:53], v[42:43], v[52:53]
	v_pk_add_f32 v[58:59], v[40:41], v[58:59]
	v_cvt_pk_bf16_f32 v40, v56, v57
	v_cvt_pk_bf16_f32 v41, v50, v51
	v_mul_f32_e32 v57, v57, v57
	v_cvt_pk_bf16_f32 v42, v58, v59
	v_cvt_pk_bf16_f32 v43, v52, v53
	s_nop 1
	s_waitcnt vmcnt(14)
	v_mul_f32_e32 v51, v51, v51
	v_mul_f32_e32 v59, v59, v59
	v_fmac_f32_e32 v57, v56, v56
	v_fmac_f32_e32 v51, v50, v50
	v_mul_f32_e32 v53, v53, v53
	v_fmac_f32_e32 v59, v58, v58
	v_add_f32_e32 v50, v57, v51
	v_fmac_f32_e32 v53, v52, v52
	v_add_f32_e32 v50, v59, v50
	v_add_f32_e32 v56, v53, v50
	global_store_dwordx4 v[54:55], v[40:43], off
	s_nop 0
	v_lshlrev_b32_e32 v50, 16, v216
	v_and_b32_e32 v51, 0xffff0000, v216
	v_lshlrev_b32_e32 v44, 16, v217
	v_and_b32_e32 v45, 0xffff0000, v217
	v_lshlrev_b32_e32 v52, 16, v218
	v_and_b32_e32 v53, 0xffff0000, v218
	v_lshlrev_b32_e32 v46, 16, v219
	v_and_b32_e32 v47, 0xffff0000, v219
	v_pk_add_f32 v[38:39], v[38:39], v[44:45]
	v_pk_add_f32 v[36:37], v[36:37], v[50:51]
	v_pk_add_f32 v[44:45], v[34:35], v[46:47]
	v_pk_add_f32 v[46:47], v[32:33], v[52:53]
	v_mul_f32_e32 v32, v37, v37
	v_mul_f32_e32 v33, v39, v39
	v_mul_f32_e32 v34, v47, v47
	v_fmac_f32_e32 v32, v36, v36
	v_fmac_f32_e32 v33, v38, v38
	v_mul_f32_e32 v35, v45, v45
	v_fmac_f32_e32 v34, v46, v46
	v_add_f32_e32 v32, v32, v33
	v_add_f32_e32 v32, v34, v32
	v_fmac_f32_e32 v35, v44, v44
	v_add_f32_e32 v32, v35, v32
	v_add_f32_e32 v32, v56, v32
	ds_bpermute_b32 v33, v114, v32
	v_cvt_pk_bf16_f32 v34, v36, v37
	v_cvt_pk_bf16_f32 v35, v38, v39
	v_cvt_pk_bf16_f32 v36, v46, v47
	v_cvt_pk_bf16_f32 v37, v44, v45
	s_waitcnt lgkmcnt(0)
	v_add_f32_e32 v32, v32, v33
	ds_bpermute_b32 v33, v115, v32
	global_store_dwordx4 v[54:55], v[34:37], off offset:64
	s_and_saveexec_b64 s[22:23], s[2:3]
	s_cbranch_execz .LBB0_343
	v_lshl_add_u64 v[34:35], v[48:49], 2, s[8:9]
	s_waitcnt lgkmcnt(0)
	v_add_f32_e32 v32, v32, v33
	global_atomic_add_f32 v[34:35], v32, off
; __device__ __forceinline__ u32x4 pack8(f32x4 a, f32x4 b) { u32x4 w; w.x = cvt_pk_bf16(a[0], a[1]); w.y = cvt_pk_bf16(a[2], a[3]); w.z = cvt_pk_bf16(b[0], b[1]); w.w = cvt_pk_bf16(b[2], b[3]); return w; }
;     __device__ __forceinline__ void operator()(const f32x4 (&acc)[2][2][4][2], const Unit& u, int wr, int wc, int fr, int fq) const {
;     ...
;         for (int ai = 0; ai < 2; ++ai)
; #pragma unroll
;             for (int m = 0; m < 4; ++m) {
;                 const int row = row0 + ai * HALF + m * 16; const size_t off = (size_t)row * 2048 + col;
;                 float s = 0.f;
; #pragma unroll
;                 for (int bj = 0; bj < 2; ++bj) {
;                     f32x4 b0, b1;
;                     if (BASE_F32) { const float* bp = (const float*)base + off + bj * 32; b0 = *(const f32x4*)bp; b1 = *(const f32x4*)(bp + 4); }
;                     else { const u32x4 w = *(const u32x4*)((const bf16_t*)base + off + bj * 32);
;                         b0 = (f32x4){__uint_as_float(w.x << 16), __uint_as_float(w.x & 0xffff0000u), __uint_as_float(w.y << 16), __uint_as_float(w.y & 0xffff0000u)};
;                         b1 = (f32x4){__uint_as_float(w.z << 16), __uint_as_float(w.z & 0xffff0000u), __uint_as_float(w.w << 16), __uint_as_float(w.w & 0xffff0000u)}; }
;                     const f32x4 h0 = b0 + acc[ai][bj][m][0], h1 = b1 + acc[ai][bj][m][1];
;                     s += (h0[0] * h0[0] + h0[1] * h0[1]) + (h0[2] * h0[2] + h0[3] * h0[3]) + (h1[0] * h1[0] + h1[1] * h1[1]) + (h1[2] * h1[2] + h1[3] * h1[3]);
;                     *(u32x4*)(H + off + bj * 32) = pack8(h0, h1);
;                 }
;                 s += __shfl_xor(s, 16); s += __shfl_xor(s, 32);
;                 if (fq == 0) __hip_atomic_fetch_add(ss + row, s, __ATOMIC_RELAXED, __HIP_MEMORY_SCOPE_AGENT);
;                 if (m & 1) asm volatile("" ::: "memory");
;             }
.LBB0_343:
	s_or_b64 exec, exec, s[22:23]
	v_add_u32_e32 v32, 0xa0, v136
	s_waitcnt lgkmcnt(0)
	v_ashrrev_i32_e32 v33, 31, v32
	v_lshlrev_b64 v[34:35], 12, v[32:33]
	v_lshl_add_u64 v[34:35], s[6:7], 0, v[34:35]
	v_lshl_add_u64 v[38:39], v[134:135], 1, v[34:35]
	s_nop 1
	s_waitcnt vmcnt(14)
	s_nop 0
	v_lshlrev_b32_e32 v40, 16, v152
	v_and_b32_e32 v41, 0xffff0000, v152
	v_lshlrev_b32_e32 v34, 16, v153
	v_and_b32_e32 v35, 0xffff0000, v153
	v_lshlrev_b32_e32 v42, 16, v154
	v_and_b32_e32 v43, 0xffff0000, v154
	v_lshlrev_b32_e32 v36, 16, v155
	v_and_b32_e32 v37, 0xffff0000, v155
	v_pk_add_f32 v[34:35], v[30:31], v[34:35]
	v_pk_add_f32 v[40:41], v[28:29], v[40:41]
	v_pk_add_f32 v[36:37], v[26:27], v[36:37]
	v_pk_add_f32 v[42:43], v[24:25], v[42:43]
	v_cvt_pk_bf16_f32 v24, v40, v41
	v_cvt_pk_bf16_f32 v25, v34, v35
	v_mul_f32_e32 v41, v41, v41
	v_cvt_pk_bf16_f32 v26, v42, v43
	v_cvt_pk_bf16_f32 v27, v36, v37
	s_nop 1
	s_waitcnt vmcnt(13)
	v_mul_f32_e32 v35, v35, v35
	v_mul_f32_e32 v43, v43, v43
	v_fmac_f32_e32 v41, v40, v40
	v_fmac_f32_e32 v35, v34, v34
	v_mul_f32_e32 v37, v37, v37
	v_fmac_f32_e32 v43, v42, v42
	v_add_f32_e32 v34, v41, v35
	v_fmac_f32_e32 v37, v36, v36
	v_add_f32_e32 v34, v43, v34
	v_add_f32_e32 v40, v37, v34
	global_store_dwordx4 v[38:39], v[24:27], off
	s_nop 0
	v_lshlrev_b32_e32 v34, 16, v156
	v_and_b32_e32 v35, 0xffff0000, v156
	v_lshlrev_b32_e32 v28, 16, v157
	v_and_b32_e32 v29, 0xffff0000, v157
	v_lshlrev_b32_e32 v36, 16, v158
	v_and_b32_e32 v37, 0xffff0000, v158
	v_lshlrev_b32_e32 v30, 16, v159
	v_and_b32_e32 v31, 0xffff0000, v159
	v_pk_add_f32 v[22:23], v[22:23], v[28:29]
	v_pk_add_f32 v[20:21], v[20:21], v[34:35]
	v_pk_add_f32 v[28:29], v[18:19], v[30:31]
	v_pk_add_f32 v[30:31], v[16:17], v[36:37]
	v_mul_f32_e32 v16, v21, v21
	v_mul_f32_e32 v17, v23, v23
	v_mul_f32_e32 v18, v31, v31
	v_fmac_f32_e32 v16, v20, v20
	v_fmac_f32_e32 v17, v22, v22
	v_mul_f32_e32 v19, v29, v29
	v_fmac_f32_e32 v18, v30, v30
	v_add_f32_e32 v16, v16, v17
	v_add_f32_e32 v16, v18, v16
	v_fmac_f32_e32 v19, v28, v28
	v_add_f32_e32 v16, v19, v16
	v_add_f32_e32 v16, v40, v16
	ds_bpermute_b32 v17, v114, v16
	v_cvt_pk_bf16_f32 v18, v20, v21
	v_cvt_pk_bf16_f32 v19, v22, v23
	v_cvt_pk_bf16_f32 v20, v30, v31
	v_cvt_pk_bf16_f32 v21, v28, v29
	s_waitcnt lgkmcnt(0)
	v_add_f32_e32 v16, v16, v17
	ds_bpermute_b32 v17, v115, v16
	global_store_dwordx4 v[38:39], v[18:21], off offset:64
	s_and_saveexec_b64 s[22:23], s[2:3]
	s_cbranch_execz .LBB0_345
	v_lshl_add_u64 v[18:19], v[32:33], 2, s[8:9]
	s_waitcnt lgkmcnt(0)
	v_add_f32_e32 v16, v16, v17
	global_atomic_add_f32 v[18:19], v16, off
.LBB0_345:
	s_or_b64 exec, exec, s[22:23]
	v_add_u32_e32 v16, 0xb0, v136
	s_waitcnt lgkmcnt(0)
	v_ashrrev_i32_e32 v17, 31, v16
	v_lshlrev_b64 v[18:19], 12, v[16:17]
	v_lshl_add_u64 v[18:19], s[6:7], 0, v[18:19]
	v_lshl_add_u64 v[22:23], v[134:135], 1, v[18:19]
	s_nop 1
	s_waitcnt vmcnt(12)
	s_nop 0
	v_lshlrev_b32_e32 v24, 16, v160
	v_and_b32_e32 v25, 0xffff0000, v160
	v_lshlrev_b32_e32 v18, 16, v161
	v_and_b32_e32 v19, 0xffff0000, v161
	v_lshlrev_b32_e32 v26, 16, v162
	v_and_b32_e32 v27, 0xffff0000, v162
	v_lshlrev_b32_e32 v20, 16, v163
	v_and_b32_e32 v21, 0xffff0000, v163
	v_pk_add_f32 v[18:19], v[14:15], v[18:19]
	v_pk_add_f32 v[24:25], v[12:13], v[24:25]
	v_pk_add_f32 v[20:21], v[10:11], v[20:21]
	v_pk_add_f32 v[26:27], v[8:9], v[26:27]
	v_cvt_pk_bf16_f32 v8, v24, v25
	v_cvt_pk_bf16_f32 v9, v18, v19
	v_mul_f32_e32 v25, v25, v25
	v_cvt_pk_bf16_f32 v10, v26, v27
	v_cvt_pk_bf16_f32 v11, v20, v21
	s_nop 1
	s_waitcnt vmcnt(11)
	v_mul_f32_e32 v19, v19, v19
	v_mul_f32_e32 v27, v27, v27
	v_fmac_f32_e32 v25, v24, v24
	v_fmac_f32_e32 v19, v18, v18
	v_mul_f32_e32 v21, v21, v21
	v_fmac_f32_e32 v27, v26, v26
	v_add_f32_e32 v18, v25, v19
	v_fmac_f32_e32 v21, v20, v20
	v_add_f32_e32 v18, v27, v18
	v_add_f32_e32 v24, v21, v18
	global_store_dwordx4 v[22:23], v[8:11], off
	s_nop 0
	v_lshlrev_b32_e32 v18, 16, v164
	v_and_b32_e32 v19, 0xffff0000, v164
	v_lshlrev_b32_e32 v12, 16, v165
	v_and_b32_e32 v13, 0xffff0000, v165
	v_lshlrev_b32_e32 v20, 16, v166
	v_and_b32_e32 v21, 0xffff0000, v166
	v_lshlrev_b32_e32 v14, 16, v167
	v_and_b32_e32 v15, 0xffff0000, v167
	v_pk_add_f32 v[6:7], v[6:7], v[12:13]
	v_pk_add_f32 v[4:5], v[4:5], v[18:19]
	v_pk_add_f32 v[12:13], v[2:3], v[14:15]
	v_pk_add_f32 v[14:15], v[0:1], v[20:21]
	v_mul_f32_e32 v0, v5, v5
	v_mul_f32_e32 v1, v7, v7
	v_mul_f32_e32 v2, v15, v15
	v_fmac_f32_e32 v0, v4, v4
	v_fmac_f32_e32 v1, v6, v6
	v_mul_f32_e32 v3, v13, v13
	v_fmac_f32_e32 v2, v14, v14
	v_add_f32_e32 v0, v0, v1
	v_add_f32_e32 v0, v2, v0
	v_fmac_f32_e32 v3, v12, v12
	v_add_f32_e32 v0, v3, v0
	v_add_f32_e32 v0, v24, v0
	ds_bpermute_b32 v1, v114, v0
	v_cvt_pk_bf16_f32 v2, v4, v5
	v_cvt_pk_bf16_f32 v3, v6, v7
	v_cvt_pk_bf16_f32 v4, v14, v15
	v_cvt_pk_bf16_f32 v5, v12, v13
	s_waitcnt lgkmcnt(0)
	v_add_f32_e32 v0, v0, v1
	ds_bpermute_b32 v1, v115, v0
	global_store_dwordx4 v[22:23], v[2:5], off offset:64
	s_and_saveexec_b64 s[22:23], s[2:3]
	s_cbranch_execz .LBB0_347
	v_lshl_add_u64 v[2:3], v[16:17], 2, s[8:9]
	s_waitcnt lgkmcnt(0)
	v_add_f32_e32 v0, v0, v1
	global_atomic_add_f32 v[2:3], v0, off

; __device__ __forceinline__ u32x4 pack8(f32x4 a, f32x4 b) { u32x4 w; w.x = cvt_pk_bf16(a[0], a[1]); w.y = cvt_pk_bf16(a[2], a[3]); w.z = cvt_pk_bf16(b[0], b[1]); w.w = cvt_pk_bf16(b[2], b[3]); return w; }
;     __device__ __forceinline__ void operator()(const f32x4 (&acc)[2][2][4][2], const Unit& u, int wr, int wc, int fr, int fq) const {
;     ...
;         for (int ai = 0; ai < 2; ++ai)
; #pragma unroll
;             for (int m = 0; m < 4; ++m) {
;                 const int row = row0 + ai * HALF + m * 16; const size_t off = (size_t)row * 2048 + col;
;                 float s = 0.f;
; #pragma unroll
;                 for (int bj = 0; bj < 2; ++bj) {
;                     f32x4 b0, b1;
;                     if (BASE_F32) { const float* bp = (const float*)base + off + bj * 32; b0 = *(const f32x4*)bp; b1 = *(const f32x4*)(bp + 4); }
;                     else { const u32x4 w = *(const u32x4*)((const bf16_t*)base + off + bj * 32);
;                         b0 = (f32x4){__uint_as_float(w.x << 16), __uint_as_float(w.x & 0xffff0000u), __uint_as_float(w.y << 16), __uint_as_float(w.y & 0xffff0000u)};
;                         b1 = (f32x4){__uint_as_float(w.z << 16), __uint_as_float(w.z & 0xffff0000u), __uint_as_float(w.w << 16), __uint_as_float(w.w & 0xffff0000u)}; }
;                     const f32x4 h0 = b0 + acc[ai][bj][m][0], h1 = b1 + acc[ai][bj][m][1];
;                     s += (h0[0] * h0[0] + h0[1] * h0[1]) + (h0[2] * h0[2] + h0[3] * h0[3]) + (h1[0] * h1[0] + h1[1] * h1[1]) + (h1[2] * h1[2] + h1[3] * h1[3]);
;                     *(u32x4*)(H + off + bj * 32) = pack8(h0, h1);
;                 }
;                 s += __shfl_xor(s, 16); s += __shfl_xor(s, 32);
;                 if (fq == 0) __hip_atomic_fetch_add(ss + row, s, __ATOMIC_RELAXED, __HIP_MEMORY_SCOPE_AGENT);
;                 if (m & 1) asm volatile("" ::: "memory");
;             }
.LBB0_620:
	v_lshl_add_u32 v136, s26, 8, v139
	v_ashrrev_i32_e32 v137, 31, v136
	v_lshl_or_b32 v134, s28, 8, v141
	v_lshlrev_b64 v[144:145], 12, v[136:137]
	v_ashrrev_i32_e32 v135, 31, v134
	v_lshl_add_u64 v[144:145], s[10:11], 0, v[144:145]
	v_lshl_add_u64 v[148:149], v[134:135], 1, v[144:145]
	v_mov_b32_e32 v170, v136
	v_ashrrev_i32_e32 v171, 31, v170
	v_lshlrev_b64 v[170:171], 12, v[170:171]
	v_lshl_add_u64 v[170:171], s[10:11], 0, v[170:171]
	v_lshl_add_u64 v[170:171], v[134:135], 1, v[170:171]
	global_load_dwordx4 v[154:157], v[170:171], off
	global_load_dwordx4 v[158:161], v[170:171], off offset:64
	v_add_u32_e32 v170, 0x10, v136
	v_ashrrev_i32_e32 v171, 31, v170
	v_lshlrev_b64 v[170:171], 12, v[170:171]
	v_lshl_add_u64 v[170:171], s[10:11], 0, v[170:171]
	v_lshl_add_u64 v[170:171], v[134:135], 1, v[170:171]
	global_load_dwordx4 v[162:165], v[170:171], off
	global_load_dwordx4 v[166:169], v[170:171], off offset:64
	v_add_u32_e32 v170, 0x20, v136
	v_ashrrev_i32_e32 v171, 31, v170
	v_lshlrev_b64 v[170:171], 12, v[170:171]
	v_lshl_add_u64 v[170:171], s[10:11], 0, v[170:171]
	v_lshl_add_u64 v[170:171], v[134:135], 1, v[170:171]
	global_load_dwordx4 v[182:185], v[170:171], off
	global_load_dwordx4 v[186:189], v[170:171], off offset:64
	v_add_u32_e32 v170, 0x30, v136
	v_ashrrev_i32_e32 v171, 31, v170
	v_lshlrev_b64 v[170:171], 12, v[170:171]
	v_lshl_add_u64 v[170:171], s[10:11], 0, v[170:171]
	v_lshl_add_u64 v[170:171], v[134:135], 1, v[170:171]
	global_load_dwordx4 v[190:193], v[170:171], off
	global_load_dwordx4 v[194:197], v[170:171], off offset:64
	v_add_u32_e32 v170, 0x80, v136
	v_ashrrev_i32_e32 v171, 31, v170
	v_lshlrev_b64 v[170:171], 12, v[170:171]
	v_lshl_add_u64 v[170:171], s[10:11], 0, v[170:171]
	v_lshl_add_u64 v[170:171], v[134:135], 1, v[170:171]
	global_load_dwordx4 v[198:201], v[170:171], off
	global_load_dwordx4 v[212:215], v[170:171], off offset:64
	v_add_u32_e32 v170, 0x90, v136
	v_ashrrev_i32_e32 v171, 31, v170
	v_lshlrev_b64 v[170:171], 12, v[170:171]
	v_lshl_add_u64 v[170:171], s[10:11], 0, v[170:171]
	v_lshl_add_u64 v[170:171], v[134:135], 1, v[170:171]
	global_load_dwordx4 v[216:219], v[170:171], off
	global_load_dwordx4 v[220:223], v[170:171], off offset:64
	s_nop 1
	s_waitcnt vmcnt(11)
	s_nop 0
	v_lshlrev_b32_e32 v150, 16, v154
	v_and_b32_e32 v151, 0xffff0000, v154
	v_lshlrev_b32_e32 v144, 16, v155
	v_and_b32_e32 v145, 0xffff0000, v155
	v_lshlrev_b32_e32 v152, 16, v156
	v_and_b32_e32 v153, 0xffff0000, v156
	v_lshlrev_b32_e32 v146, 16, v157
	v_and_b32_e32 v147, 0xffff0000, v157
	v_pk_add_f32 v[126:127], v[126:127], v[144:145]
	v_pk_add_f32 v[124:125], v[124:125], v[150:151]
	v_pk_add_f32 v[144:145], v[122:123], v[146:147]
	v_pk_add_f32 v[122:123], v[120:121], v[152:153]
	v_mul_f32_e32 v120, v125, v125
	v_mul_f32_e32 v121, v127, v127
	v_fmac_f32_e32 v120, v124, v124
	v_fmac_f32_e32 v121, v126, v126
	v_add_f32_e32 v120, v120, v121
	v_mul_f32_e32 v121, v123, v123
	v_fmac_f32_e32 v121, v122, v122
	v_add_f32_e32 v120, v121, v120
	v_mul_f32_e32 v121, v145, v145
	v_fmac_f32_e32 v121, v144, v144
	v_add_f32_e32 v143, v121, v120
	v_cvt_pk_bf16_f32 v120, v124, v125
	v_cvt_pk_bf16_f32 v121, v126, v127
	v_cvt_pk_bf16_f32 v122, v122, v123
	v_cvt_pk_bf16_f32 v123, v144, v145
	global_store_dwordx4 v[148:149], v[120:123], off
	s_nop 1
	s_waitcnt vmcnt(11)
	s_nop 0
	v_lshlrev_b32_e32 v124, 16, v158
	v_and_b32_e32 v125, 0xffff0000, v158
	v_lshlrev_b32_e32 v120, 16, v159
	v_and_b32_e32 v121, 0xffff0000, v159
	v_lshlrev_b32_e32 v126, 16, v160
	v_and_b32_e32 v127, 0xffff0000, v160
	v_lshlrev_b32_e32 v122, 16, v161
	v_and_b32_e32 v123, 0xffff0000, v161
	v_add_u32_e32 v170, 0xa0, v136
	v_ashrrev_i32_e32 v171, 31, v170
	v_lshlrev_b64 v[170:171], 12, v[170:171]
	v_lshl_add_u64 v[170:171], s[10:11], 0, v[170:171]
	v_lshl_add_u64 v[170:171], v[134:135], 1, v[170:171]
	global_load_dwordx4 v[154:157], v[170:171], off
	global_load_dwordx4 v[158:161], v[170:171], off offset:64
	v_pk_add_f32 v[118:119], v[118:119], v[120:121]
	v_pk_add_f32 v[116:117], v[116:117], v[124:125]
	v_pk_add_f32 v[120:121], v[114:115], v[122:123]
	v_pk_add_f32 v[114:115], v[112:113], v[126:127]
	v_mul_f32_e32 v112, v117, v117
	v_mul_f32_e32 v113, v119, v119
	v_fmac_f32_e32 v112, v116, v116
	v_fmac_f32_e32 v113, v118, v118
	v_add_f32_e32 v112, v112, v113
	v_mul_f32_e32 v113, v115, v115
	v_fmac_f32_e32 v113, v114, v114
	v_add_f32_e32 v112, v113, v112
	v_mul_f32_e32 v113, v121, v121
	v_fmac_f32_e32 v113, v120, v120
	v_add_f32_e32 v112, v113, v112
	v_add_f32_e32 v122, v143, v112
	v_cvt_pk_bf16_f32 v112, v116, v117
	v_cvt_pk_bf16_f32 v113, v118, v119
	v_cvt_pk_bf16_f32 v114, v114, v115
	v_cvt_pk_bf16_f32 v115, v120, v121
	global_store_dwordx4 v[148:149], v[112:115], off offset:64
	s_nop 1
	v_and_b32_e32 v113, 64, v209
	v_xor_b32_e32 v112, 16, v209
	v_add_u32_e32 v113, 64, v113
	v_cmp_lt_i32_e32 vcc, v112, v113
	v_xor_b32_e32 v115, 32, v209
	s_nop 0
	v_cndmask_b32_e32 v112, v209, v112, vcc
	v_lshlrev_b32_e32 v114, 2, v112
	ds_bpermute_b32 v112, v114, v122
	v_cmp_lt_i32_e32 vcc, v115, v113
	s_waitcnt lgkmcnt(0)
	v_add_f32_e32 v112, v122, v112
	v_cndmask_b32_e32 v113, v209, v115, vcc
	v_lshlrev_b32_e32 v115, 2, v113
	ds_bpermute_b32 v113, v115, v112
	s_and_saveexec_b64 s[26:27], s[2:3]
	s_cbranch_execz .LBB0_622
	v_lshl_add_u64 v[116:117], v[136:137], 2, s[12:13]
	s_waitcnt lgkmcnt(0)
	v_add_f32_e32 v112, v112, v113
	global_atomic_add_f32 v[116:117], v112, off
; __device__ __forceinline__ u32x4 pack8(f32x4 a, f32x4 b) { u32x4 w; w.x = cvt_pk_bf16(a[0], a[1]); w.y = cvt_pk_bf16(a[2], a[3]); w.z = cvt_pk_bf16(b[0], b[1]); w.w = cvt_pk_bf16(b[2], b[3]); return w; }
;     __device__ __forceinline__ void operator()(const f32x4 (&acc)[2][2][4][2], const Unit& u, int wr, int wc, int fr, int fq) const {
;     ...
;         for (int ai = 0; ai < 2; ++ai)
; #pragma unroll
;             for (int m = 0; m < 4; ++m) {
;                 const int row = row0 + ai * HALF + m * 16; const size_t off = (size_t)row * 2048 + col;
;                 float s = 0.f;
; #pragma unroll
;                 for (int bj = 0; bj < 2; ++bj) {
;                     f32x4 b0, b1;
;                     if (BASE_F32) { const float* bp = (const float*)base + off + bj * 32; b0 = *(const f32x4*)bp; b1 = *(const f32x4*)(bp + 4); }
;                     else { const u32x4 w = *(const u32x4*)((const bf16_t*)base + off + bj * 32);
;                         b0 = (f32x4){__uint_as_float(w.x << 16), __uint_as_float(w.x & 0xffff0000u), __uint_as_float(w.y << 16), __uint_as_float(w.y & 0xffff0000u)};
;                         b1 = (f32x4){__uint_as_float(w.z << 16), __uint_as_float(w.z & 0xffff0000u), __uint_as_float(w.w << 16), __uint_as_float(w.w & 0xffff0000u)}; }
;                     const f32x4 h0 = b0 + acc[ai][bj][m][0], h1 = b1 + acc[ai][bj][m][1];
;                     s += (h0[0] * h0[0] + h0[1] * h0[1]) + (h0[2] * h0[2] + h0[3] * h0[3]) + (h1[0] * h1[0] + h1[1] * h1[1]) + (h1[2] * h1[2] + h1[3] * h1[3]);
;                     *(u32x4*)(H + off + bj * 32) = pack8(h0, h1);
;                 }
;                 s += __shfl_xor(s, 16); s += __shfl_xor(s, 32);
;                 if (fq == 0) __hip_atomic_fetch_add(ss + row, s, __ATOMIC_RELAXED, __HIP_MEMORY_SCOPE_AGENT);
;                 if (m & 1) asm volatile("" ::: "memory");
;             }
.LBB0_622:
	s_or_b64 exec, exec, s[26:27]
	v_or_b32_e32 v112, 16, v136
	s_waitcnt lgkmcnt(0)
	v_ashrrev_i32_e32 v113, 31, v112
	v_lshlrev_b64 v[116:117], 12, v[112:113]
	v_lshl_add_u64 v[116:117], s[10:11], 0, v[116:117]
	v_lshl_add_u64 v[120:121], v[134:135], 1, v[116:117]
	s_nop 1
	s_waitcnt vmcnt(13)
	s_nop 0
	v_lshlrev_b32_e32 v122, 16, v162
	v_and_b32_e32 v123, 0xffff0000, v162
	v_lshlrev_b32_e32 v116, 16, v163
	v_and_b32_e32 v117, 0xffff0000, v163
	v_lshlrev_b32_e32 v124, 16, v164
	v_and_b32_e32 v125, 0xffff0000, v164
	v_lshlrev_b32_e32 v118, 16, v165
	v_and_b32_e32 v119, 0xffff0000, v165
	v_pk_add_f32 v[116:117], v[110:111], v[116:117]
	v_pk_add_f32 v[122:123], v[108:109], v[122:123]
	v_pk_add_f32 v[118:119], v[106:107], v[118:119]
	v_pk_add_f32 v[124:125], v[104:105], v[124:125]
	v_cvt_pk_bf16_f32 v104, v122, v123
	v_cvt_pk_bf16_f32 v105, v116, v117
	v_mul_f32_e32 v123, v123, v123
	v_cvt_pk_bf16_f32 v106, v124, v125
	v_cvt_pk_bf16_f32 v107, v118, v119
	s_nop 1
	s_waitcnt vmcnt(12)
	v_mul_f32_e32 v117, v117, v117
	v_mul_f32_e32 v125, v125, v125
	v_fmac_f32_e32 v123, v122, v122
	v_fmac_f32_e32 v117, v116, v116
	v_mul_f32_e32 v119, v119, v119
	v_fmac_f32_e32 v125, v124, v124
	v_add_f32_e32 v116, v123, v117
	v_fmac_f32_e32 v119, v118, v118
	v_add_f32_e32 v116, v125, v116
	v_add_f32_e32 v122, v119, v116
	global_store_dwordx4 v[120:121], v[104:107], off
	s_nop 0
	v_lshlrev_b32_e32 v116, 16, v166
	v_and_b32_e32 v117, 0xffff0000, v166
	v_lshlrev_b32_e32 v108, 16, v167
	v_and_b32_e32 v109, 0xffff0000, v167
	v_lshlrev_b32_e32 v118, 16, v168
	v_and_b32_e32 v119, 0xffff0000, v168
	v_lshlrev_b32_e32 v110, 16, v169
	v_and_b32_e32 v111, 0xffff0000, v169
	v_add_u32_e32 v170, 0xb0, v136
	v_ashrrev_i32_e32 v171, 31, v170
	v_lshlrev_b64 v[170:171], 12, v[170:171]
	v_lshl_add_u64 v[170:171], s[10:11], 0, v[170:171]
	v_lshl_add_u64 v[170:171], v[134:135], 1, v[170:171]
	global_load_dwordx4 v[162:165], v[170:171], off
	global_load_dwordx4 v[166:169], v[170:171], off offset:64
	v_pk_add_f32 v[102:103], v[102:103], v[108:109]
	v_pk_add_f32 v[100:101], v[100:101], v[116:117]
	v_pk_add_f32 v[108:109], v[98:99], v[110:111]
	v_pk_add_f32 v[110:111], v[96:97], v[118:119]
	v_mul_f32_e32 v96, v101, v101
	v_mul_f32_e32 v97, v103, v103
	v_mul_f32_e32 v98, v111, v111
	v_fmac_f32_e32 v96, v100, v100
	v_fmac_f32_e32 v97, v102, v102
	v_mul_f32_e32 v99, v109, v109
	v_fmac_f32_e32 v98, v110, v110
	v_add_f32_e32 v96, v96, v97
	v_add_f32_e32 v96, v98, v96
	v_fmac_f32_e32 v99, v108, v108
	v_add_f32_e32 v96, v99, v96
	v_add_f32_e32 v96, v122, v96
	ds_bpermute_b32 v97, v114, v96
	v_cvt_pk_bf16_f32 v98, v100, v101
	v_cvt_pk_bf16_f32 v99, v102, v103
	v_cvt_pk_bf16_f32 v100, v110, v111
	v_cvt_pk_bf16_f32 v101, v108, v109
	s_waitcnt lgkmcnt(0)
	v_add_f32_e32 v96, v96, v97
	ds_bpermute_b32 v97, v115, v96
	global_store_dwordx4 v[120:121], v[98:101], off offset:64
	s_and_saveexec_b64 s[26:27], s[2:3]
	s_cbranch_execz .LBB0_624
	v_lshl_add_u64 v[98:99], v[112:113], 2, s[12:13]
	s_waitcnt lgkmcnt(0)
	v_add_f32_e32 v96, v96, v97
	global_atomic_add_f32 v[98:99], v96, off
.LBB0_624:
	s_or_b64 exec, exec, s[26:27]
	v_or_b32_e32 v96, 32, v136
	s_waitcnt lgkmcnt(0)
	v_ashrrev_i32_e32 v97, 31, v96
	v_lshlrev_b64 v[98:99], 12, v[96:97]
	v_lshl_add_u64 v[98:99], s[10:11], 0, v[98:99]
	v_lshl_add_u64 v[102:103], v[134:135], 1, v[98:99]
	s_nop 1
	s_waitcnt vmcnt(15)
	s_nop 0
	v_lshlrev_b32_e32 v104, 16, v182
	v_and_b32_e32 v105, 0xffff0000, v182
	v_lshlrev_b32_e32 v98, 16, v183
	v_and_b32_e32 v99, 0xffff0000, v183
	v_lshlrev_b32_e32 v106, 16, v184
	v_and_b32_e32 v107, 0xffff0000, v184
	v_lshlrev_b32_e32 v100, 16, v185
	v_and_b32_e32 v101, 0xffff0000, v185
	v_pk_add_f32 v[98:99], v[94:95], v[98:99]
	v_pk_add_f32 v[104:105], v[92:93], v[104:105]
	v_pk_add_f32 v[100:101], v[90:91], v[100:101]
	v_pk_add_f32 v[106:107], v[88:89], v[106:107]
	v_cvt_pk_bf16_f32 v88, v104, v105
	v_cvt_pk_bf16_f32 v89, v98, v99
	v_mul_f32_e32 v105, v105, v105
	v_cvt_pk_bf16_f32 v90, v106, v107
	v_cvt_pk_bf16_f32 v91, v100, v101
	s_nop 1
	s_waitcnt vmcnt(14)
	v_mul_f32_e32 v99, v99, v99
	v_mul_f32_e32 v107, v107, v107
	v_fmac_f32_e32 v105, v104, v104
	v_fmac_f32_e32 v99, v98, v98
	v_mul_f32_e32 v101, v101, v101
	v_fmac_f32_e32 v107, v106, v106
	v_add_f32_e32 v98, v105, v99
	v_fmac_f32_e32 v101, v100, v100
	v_add_f32_e32 v98, v107, v98
	v_add_f32_e32 v104, v101, v98
	global_store_dwordx4 v[102:103], v[88:91], off
	s_nop 0
	v_lshlrev_b32_e32 v98, 16, v186
	v_and_b32_e32 v99, 0xffff0000, v186
	v_lshlrev_b32_e32 v92, 16, v187
	v_and_b32_e32 v93, 0xffff0000, v187
	v_lshlrev_b32_e32 v100, 16, v188
	v_and_b32_e32 v101, 0xffff0000, v188
	v_lshlrev_b32_e32 v94, 16, v189
	v_and_b32_e32 v95, 0xffff0000, v189
	v_pk_add_f32 v[86:87], v[86:87], v[92:93]
	v_pk_add_f32 v[84:85], v[84:85], v[98:99]
	v_pk_add_f32 v[92:93], v[82:83], v[94:95]
	v_pk_add_f32 v[94:95], v[80:81], v[100:101]
	v_mul_f32_e32 v80, v85, v85
	v_mul_f32_e32 v81, v87, v87
	v_mul_f32_e32 v82, v95, v95
	v_fmac_f32_e32 v80, v84, v84
	v_fmac_f32_e32 v81, v86, v86
	v_mul_f32_e32 v83, v93, v93
	v_fmac_f32_e32 v82, v94, v94
	v_add_f32_e32 v80, v80, v81
	v_add_f32_e32 v80, v82, v80
	v_fmac_f32_e32 v83, v92, v92
	v_add_f32_e32 v80, v83, v80
	v_add_f32_e32 v80, v104, v80
	ds_bpermute_b32 v81, v114, v80
	v_cvt_pk_bf16_f32 v82, v84, v85
	v_cvt_pk_bf16_f32 v83, v86, v87
	v_cvt_pk_bf16_f32 v84, v94, v95
	v_cvt_pk_bf16_f32 v85, v92, v93
	s_waitcnt lgkmcnt(0)
	v_add_f32_e32 v80, v80, v81
	ds_bpermute_b32 v81, v115, v80
	global_store_dwordx4 v[102:103], v[82:85], off offset:64
	s_and_saveexec_b64 s[26:27], s[2:3]
	s_cbranch_execz .LBB0_626
	v_lshl_add_u64 v[82:83], v[96:97], 2, s[12:13]
	s_waitcnt lgkmcnt(0)
	v_add_f32_e32 v80, v80, v81
	global_atomic_add_f32 v[82:83], v80, off
; __device__ __forceinline__ u32x4 pack8(f32x4 a, f32x4 b) { u32x4 w; w.x = cvt_pk_bf16(a[0], a[1]); w.y = cvt_pk_bf16(a[2], a[3]); w.z = cvt_pk_bf16(b[0], b[1]); w.w = cvt_pk_bf16(b[2], b[3]); return w; }
;     __device__ __forceinline__ void operator()(const f32x4 (&acc)[2][2][4][2], const Unit& u, int wr, int wc, int fr, int fq) const {
;     ...
;         for (int ai = 0; ai < 2; ++ai)
; #pragma unroll
;             for (int m = 0; m < 4; ++m) {
;                 const int row = row0 + ai * HALF + m * 16; const size_t off = (size_t)row * 2048 + col;
;                 float s = 0.f;
; #pragma unroll
;                 for (int bj = 0; bj < 2; ++bj) {
;                     f32x4 b0, b1;
;                     if (BASE_F32) { const float* bp = (const float*)base + off + bj * 32; b0 = *(const f32x4*)bp; b1 = *(const f32x4*)(bp + 4); }
;                     else { const u32x4 w = *(const u32x4*)((const bf16_t*)base + off + bj * 32);
;                         b0 = (f32x4){__uint_as_float(w.x << 16), __uint_as_float(w.x & 0xffff0000u), __uint_as_float(w.y << 16), __uint_as_float(w.y & 0xffff0000u)};
;                         b1 = (f32x4){__uint_as_float(w.z << 16), __uint_as_float(w.z & 0xffff0000u), __uint_as_float(w.w << 16), __uint_as_float(w.w & 0xffff0000u)}; }
;                     const f32x4 h0 = b0 + acc[ai][bj][m][0], h1 = b1 + acc[ai][bj][m][1];
;                     s += (h0[0] * h0[0] + h0[1] * h0[1]) + (h0[2] * h0[2] + h0[3] * h0[3]) + (h1[0] * h1[0] + h1[1] * h1[1]) + (h1[2] * h1[2] + h1[3] * h1[3]);
;                     *(u32x4*)(H + off + bj * 32) = pack8(h0, h1);
;                 }
;                 s += __shfl_xor(s, 16); s += __shfl_xor(s, 32);
;                 if (fq == 0) __hip_atomic_fetch_add(ss + row, s, __ATOMIC_RELAXED, __HIP_MEMORY_SCOPE_AGENT);
;                 if (m & 1) asm volatile("" ::: "memory");
;             }
.LBB0_626:
	s_or_b64 exec, exec, s[26:27]
	v_or_b32_e32 v80, 48, v136
	s_waitcnt lgkmcnt(0)
	v_ashrrev_i32_e32 v81, 31, v80
	v_lshlrev_b64 v[82:83], 12, v[80:81]
	v_lshl_add_u64 v[82:83], s[10:11], 0, v[82:83]
	v_lshl_add_u64 v[86:87], v[134:135], 1, v[82:83]
	s_nop 1
	s_waitcnt vmcnt(15)
	s_nop 0
	v_lshlrev_b32_e32 v88, 16, v190
	v_and_b32_e32 v89, 0xffff0000, v190
	v_lshlrev_b32_e32 v82, 16, v191
	v_and_b32_e32 v83, 0xffff0000, v191
	v_lshlrev_b32_e32 v90, 16, v192
	v_and_b32_e32 v91, 0xffff0000, v192
	v_lshlrev_b32_e32 v84, 16, v193
	v_and_b32_e32 v85, 0xffff0000, v193
	v_pk_add_f32 v[82:83], v[78:79], v[82:83]
	v_pk_add_f32 v[88:89], v[76:77], v[88:89]
	v_pk_add_f32 v[84:85], v[74:75], v[84:85]
	v_pk_add_f32 v[90:91], v[72:73], v[90:91]
	v_cvt_pk_bf16_f32 v72, v88, v89
	v_cvt_pk_bf16_f32 v73, v82, v83
	v_mul_f32_e32 v89, v89, v89
	v_cvt_pk_bf16_f32 v74, v90, v91
	v_cvt_pk_bf16_f32 v75, v84, v85
	s_nop 1
	s_waitcnt vmcnt(14)
	v_mul_f32_e32 v83, v83, v83
	v_mul_f32_e32 v91, v91, v91
	v_fmac_f32_e32 v89, v88, v88
	v_fmac_f32_e32 v83, v82, v82
	v_mul_f32_e32 v85, v85, v85
	v_fmac_f32_e32 v91, v90, v90
	v_add_f32_e32 v82, v89, v83
	v_fmac_f32_e32 v85, v84, v84
	v_add_f32_e32 v82, v91, v82
	v_add_f32_e32 v88, v85, v82
	global_store_dwordx4 v[86:87], v[72:75], off
	s_nop 0
	v_lshlrev_b32_e32 v82, 16, v194
	v_and_b32_e32 v83, 0xffff0000, v194
	v_lshlrev_b32_e32 v76, 16, v195
	v_and_b32_e32 v77, 0xffff0000, v195
	v_lshlrev_b32_e32 v84, 16, v196
	v_and_b32_e32 v85, 0xffff0000, v196
	v_lshlrev_b32_e32 v78, 16, v197
	v_and_b32_e32 v79, 0xffff0000, v197
	v_pk_add_f32 v[70:71], v[70:71], v[76:77]
	v_pk_add_f32 v[68:69], v[68:69], v[82:83]
	v_pk_add_f32 v[76:77], v[66:67], v[78:79]
	v_pk_add_f32 v[78:79], v[64:65], v[84:85]
	v_mul_f32_e32 v64, v69, v69
	v_mul_f32_e32 v65, v71, v71
	v_mul_f32_e32 v66, v79, v79
	v_fmac_f32_e32 v64, v68, v68
	v_fmac_f32_e32 v65, v70, v70
	v_mul_f32_e32 v67, v77, v77
	v_fmac_f32_e32 v66, v78, v78
	v_add_f32_e32 v64, v64, v65
	v_add_f32_e32 v64, v66, v64
	v_fmac_f32_e32 v67, v76, v76
	v_add_f32_e32 v64, v67, v64
	v_add_f32_e32 v64, v88, v64
	ds_bpermute_b32 v65, v114, v64
	v_cvt_pk_bf16_f32 v66, v68, v69
	v_cvt_pk_bf16_f32 v67, v70, v71
	v_cvt_pk_bf16_f32 v68, v78, v79
	v_cvt_pk_bf16_f32 v69, v76, v77
	s_waitcnt lgkmcnt(0)
	v_add_f32_e32 v64, v64, v65
	ds_bpermute_b32 v65, v115, v64
	global_store_dwordx4 v[86:87], v[66:69], off offset:64
	s_and_saveexec_b64 s[26:27], s[2:3]
	s_cbranch_execz .LBB0_628
	v_lshl_add_u64 v[66:67], v[80:81], 2, s[12:13]
	s_waitcnt lgkmcnt(0)
	v_add_f32_e32 v64, v64, v65
	global_atomic_add_f32 v[66:67], v64, off
.LBB0_628:
	s_or_b64 exec, exec, s[26:27]
	v_add_u32_e32 v64, 0x80, v136
	s_waitcnt lgkmcnt(0)
	v_ashrrev_i32_e32 v65, 31, v64
	v_lshlrev_b64 v[66:67], 12, v[64:65]
	v_lshl_add_u64 v[66:67], s[10:11], 0, v[66:67]
	v_lshl_add_u64 v[70:71], v[134:135], 1, v[66:67]
	s_nop 1
	s_waitcnt vmcnt(15)
	s_nop 0
	v_lshlrev_b32_e32 v72, 16, v198
	v_and_b32_e32 v73, 0xffff0000, v198
	v_lshlrev_b32_e32 v66, 16, v199
	v_and_b32_e32 v67, 0xffff0000, v199
	v_lshlrev_b32_e32 v74, 16, v200
	v_and_b32_e32 v75, 0xffff0000, v200
	v_lshlrev_b32_e32 v68, 16, v201
	v_and_b32_e32 v69, 0xffff0000, v201
	v_pk_add_f32 v[66:67], v[62:63], v[66:67]
	v_pk_add_f32 v[72:73], v[60:61], v[72:73]
	v_pk_add_f32 v[68:69], v[58:59], v[68:69]
	v_pk_add_f32 v[74:75], v[56:57], v[74:75]
	v_cvt_pk_bf16_f32 v56, v72, v73
	v_cvt_pk_bf16_f32 v57, v66, v67
	v_mul_f32_e32 v73, v73, v73
	v_cvt_pk_bf16_f32 v58, v74, v75
	v_cvt_pk_bf16_f32 v59, v68, v69
	s_nop 1
	s_waitcnt vmcnt(14)
	v_mul_f32_e32 v67, v67, v67
	v_mul_f32_e32 v75, v75, v75
	v_fmac_f32_e32 v73, v72, v72
	v_fmac_f32_e32 v67, v66, v66
	v_mul_f32_e32 v69, v69, v69
	v_fmac_f32_e32 v75, v74, v74
	v_add_f32_e32 v66, v73, v67
	v_fmac_f32_e32 v69, v68, v68
	v_add_f32_e32 v66, v75, v66
	v_add_f32_e32 v72, v69, v66
	global_store_dwordx4 v[70:71], v[56:59], off
	s_nop 0
	v_lshlrev_b32_e32 v66, 16, v212
	v_and_b32_e32 v67, 0xffff0000, v212
	v_lshlrev_b32_e32 v60, 16, v213
	v_and_b32_e32 v61, 0xffff0000, v213
	v_lshlrev_b32_e32 v68, 16, v214
	v_and_b32_e32 v69, 0xffff0000, v214
	v_lshlrev_b32_e32 v62, 16, v215
	v_and_b32_e32 v63, 0xffff0000, v215
	v_pk_add_f32 v[54:55], v[54:55], v[60:61]
	v_pk_add_f32 v[52:53], v[52:53], v[66:67]
	v_pk_add_f32 v[60:61], v[50:51], v[62:63]
	v_pk_add_f32 v[62:63], v[48:49], v[68:69]
	v_mul_f32_e32 v48, v53, v53
	v_mul_f32_e32 v49, v55, v55
	v_mul_f32_e32 v50, v63, v63
	v_fmac_f32_e32 v48, v52, v52
	v_fmac_f32_e32 v49, v54, v54
	v_mul_f32_e32 v51, v61, v61
	v_fmac_f32_e32 v50, v62, v62
	v_add_f32_e32 v48, v48, v49
	v_add_f32_e32 v48, v50, v48
	v_fmac_f32_e32 v51, v60, v60
	v_add_f32_e32 v48, v51, v48
	v_add_f32_e32 v48, v72, v48
	ds_bpermute_b32 v49, v114, v48
	v_cvt_pk_bf16_f32 v50, v52, v53
	v_cvt_pk_bf16_f32 v51, v54, v55
	v_cvt_pk_bf16_f32 v52, v62, v63
	v_cvt_pk_bf16_f32 v53, v60, v61
	s_waitcnt lgkmcnt(0)
	v_add_f32_e32 v48, v48, v49
	ds_bpermute_b32 v49, v115, v48
	global_store_dwordx4 v[70:71], v[50:53], off offset:64
	s_and_saveexec_b64 s[26:27], s[2:3]
	s_cbranch_execz .LBB0_630
	v_lshl_add_u64 v[50:51], v[64:65], 2, s[12:13]
	s_waitcnt lgkmcnt(0)
	v_add_f32_e32 v48, v48, v49
	global_atomic_add_f32 v[50:51], v48, off
; __device__ __forceinline__ u32x4 pack8(f32x4 a, f32x4 b) { u32x4 w; w.x = cvt_pk_bf16(a[0], a[1]); w.y = cvt_pk_bf16(a[2], a[3]); w.z = cvt_pk_bf16(b[0], b[1]); w.w = cvt_pk_bf16(b[2], b[3]); return w; }
;     __device__ __forceinline__ void operator()(const f32x4 (&acc)[2][2][4][2], const Unit& u, int wr, int wc, int fr, int fq) const {
;     ...
;         for (int ai = 0; ai < 2; ++ai)
; #pragma unroll
;             for (int m = 0; m < 4; ++m) {
;                 const int row = row0 + ai * HALF + m * 16; const size_t off = (size_t)row * 2048 + col;
;                 float s = 0.f;
; #pragma unroll
;                 for (int bj = 0; bj < 2; ++bj) {
;                     f32x4 b0, b1;
;                     if (BASE_F32) { const float* bp = (const float*)base + off + bj * 32; b0 = *(const f32x4*)bp; b1 = *(const f32x4*)(bp + 4); }
;                     else { const u32x4 w = *(const u32x4*)((const bf16_t*)base + off + bj * 32);
;                         b0 = (f32x4){__uint_as_float(w.x << 16), __uint_as_float(w.x & 0xffff0000u), __uint_as_float(w.y << 16), __uint_as_float(w.y & 0xffff0000u)};
;                         b1 = (f32x4){__uint_as_float(w.z << 16), __uint_as_float(w.z & 0xffff0000u), __uint_as_float(w.w << 16), __uint_as_float(w.w & 0xffff0000u)}; }
;                     const f32x4 h0 = b0 + acc[ai][bj][m][0], h1 = b1 + acc[ai][bj][m][1];
;                     s += (h0[0] * h0[0] + h0[1] * h0[1]) + (h0[2] * h0[2] + h0[3] * h0[3]) + (h1[0] * h1[0] + h1[1] * h1[1]) + (h1[2] * h1[2] + h1[3] * h1[3]);
;                     *(u32x4*)(H + off + bj * 32) = pack8(h0, h1);
;                 }
;                 s += __shfl_xor(s, 16); s += __shfl_xor(s, 32);
;                 if (fq == 0) __hip_atomic_fetch_add(ss + row, s, __ATOMIC_RELAXED, __HIP_MEMORY_SCOPE_AGENT);
;                 if (m & 1) asm volatile("" ::: "memory");
;             }
.LBB0_630:
	s_or_b64 exec, exec, s[26:27]
	v_add_u32_e32 v48, 0x90, v136
	s_waitcnt lgkmcnt(0)
	v_ashrrev_i32_e32 v49, 31, v48
	v_lshlrev_b64 v[50:51], 12, v[48:49]
	v_lshl_add_u64 v[50:51], s[10:11], 0, v[50:51]
	v_lshl_add_u64 v[54:55], v[134:135], 1, v[50:51]
	s_nop 1
	s_waitcnt vmcnt(15)
	s_nop 0
	v_lshlrev_b32_e32 v56, 16, v216
	v_and_b32_e32 v57, 0xffff0000, v216
	v_lshlrev_b32_e32 v50, 16, v217
	v_and_b32_e32 v51, 0xffff0000, v217
	v_lshlrev_b32_e32 v58, 16, v218
	v_and_b32_e32 v59, 0xffff0000, v218
	v_lshlrev_b32_e32 v52, 16, v219
	v_and_b32_e32 v53, 0xffff0000, v219
	v_pk_add_f32 v[50:51], v[46:47], v[50:51]
	v_pk_add_f32 v[56:57], v[44:45], v[56:57]
	v_pk_add_f32 v[52:53], v[42:43], v[52:53]
	v_pk_add_f32 v[58:59], v[40:41], v[58:59]
	v_cvt_pk_bf16_f32 v40, v56, v57
	v_cvt_pk_bf16_f32 v41, v50, v51
	v_mul_f32_e32 v57, v57, v57
	v_cvt_pk_bf16_f32 v42, v58, v59
	v_cvt_pk_bf16_f32 v43, v52, v53
	s_nop 1
	s_waitcnt vmcnt(14)
	v_mul_f32_e32 v51, v51, v51
	v_mul_f32_e32 v59, v59, v59
	v_fmac_f32_e32 v57, v56, v56
	v_fmac_f32_e32 v51, v50, v50
	v_mul_f32_e32 v53, v53, v53
	v_fmac_f32_e32 v59, v58, v58
	v_add_f32_e32 v50, v57, v51
	v_fmac_f32_e32 v53, v52, v52
	v_add_f32_e32 v50, v59, v50
	v_add_f32_e32 v56, v53, v50
	global_store_dwordx4 v[54:55], v[40:43], off
	s_nop 0
	v_lshlrev_b32_e32 v50, 16, v220
	v_and_b32_e32 v51, 0xffff0000, v220
	v_lshlrev_b32_e32 v44, 16, v221
	v_and_b32_e32 v45, 0xffff0000, v221
	v_lshlrev_b32_e32 v52, 16, v222
	v_and_b32_e32 v53, 0xffff0000, v222
	v_lshlrev_b32_e32 v46, 16, v223
	v_and_b32_e32 v47, 0xffff0000, v223
	v_pk_add_f32 v[38:39], v[38:39], v[44:45]
	v_pk_add_f32 v[36:37], v[36:37], v[50:51]
	v_pk_add_f32 v[44:45], v[34:35], v[46:47]
	v_pk_add_f32 v[46:47], v[32:33], v[52:53]
	v_mul_f32_e32 v32, v37, v37
	v_mul_f32_e32 v33, v39, v39
	v_mul_f32_e32 v34, v47, v47
	v_fmac_f32_e32 v32, v36, v36
	v_fmac_f32_e32 v33, v38, v38
	v_mul_f32_e32 v35, v45, v45
	v_fmac_f32_e32 v34, v46, v46
	v_add_f32_e32 v32, v32, v33
	v_add_f32_e32 v32, v34, v32
	v_fmac_f32_e32 v35, v44, v44
	v_add_f32_e32 v32, v35, v32
	v_add_f32_e32 v32, v56, v32
	ds_bpermute_b32 v33, v114, v32
	v_cvt_pk_bf16_f32 v34, v36, v37
	v_cvt_pk_bf16_f32 v35, v38, v39
	v_cvt_pk_bf16_f32 v36, v46, v47
	v_cvt_pk_bf16_f32 v37, v44, v45
	s_waitcnt lgkmcnt(0)
	v_add_f32_e32 v32, v32, v33
	ds_bpermute_b32 v33, v115, v32
	global_store_dwordx4 v[54:55], v[34:37], off offset:64
	s_and_saveexec_b64 s[26:27], s[2:3]
	s_cbranch_execz .LBB0_632
	v_lshl_add_u64 v[34:35], v[48:49], 2, s[12:13]
	s_waitcnt lgkmcnt(0)
	v_add_f32_e32 v32, v32, v33
	global_atomic_add_f32 v[34:35], v32, off
; __device__ __forceinline__ u32x4 pack8(f32x4 a, f32x4 b) { u32x4 w; w.x = cvt_pk_bf16(a[0], a[1]); w.y = cvt_pk_bf16(a[2], a[3]); w.z = cvt_pk_bf16(b[0], b[1]); w.w = cvt_pk_bf16(b[2], b[3]); return w; }
;     __device__ __forceinline__ void operator()(const f32x4 (&acc)[2][2][4][2], const Unit& u, int wr, int wc, int fr, int fq) const {
;     ...
;         for (int ai = 0; ai < 2; ++ai)
; #pragma unroll
;             for (int m = 0; m < 4; ++m) {
;                 const int row = row0 + ai * HALF + m * 16; const size_t off = (size_t)row * 2048 + col;
;                 float s = 0.f;
; #pragma unroll
;                 for (int bj = 0; bj < 2; ++bj) {
;                     f32x4 b0, b1;
;                     if (BASE_F32) { const float* bp = (const float*)base + off + bj * 32; b0 = *(const f32x4*)bp; b1 = *(const f32x4*)(bp + 4); }
;                     else { const u32x4 w = *(const u32x4*)((const bf16_t*)base + off + bj * 32);
;                         b0 = (f32x4){__uint_as_float(w.x << 16), __uint_as_float(w.x & 0xffff0000u), __uint_as_float(w.y << 16), __uint_as_float(w.y & 0xffff0000u)};
;                         b1 = (f32x4){__uint_as_float(w.z << 16), __uint_as_float(w.z & 0xffff0000u), __uint_as_float(w.w << 16), __uint_as_float(w.w & 0xffff0000u)}; }
;                     const f32x4 h0 = b0 + acc[ai][bj][m][0], h1 = b1 + acc[ai][bj][m][1];
;                     s += (h0[0] * h0[0] + h0[1] * h0[1]) + (h0[2] * h0[2] + h0[3] * h0[3]) + (h1[0] * h1[0] + h1[1] * h1[1]) + (h1[2] * h1[2] + h1[3] * h1[3]);
;                     *(u32x4*)(H + off + bj * 32) = pack8(h0, h1);
;                 }
;                 s += __shfl_xor(s, 16); s += __shfl_xor(s, 32);
;                 if (fq == 0) __hip_atomic_fetch_add(ss + row, s, __ATOMIC_RELAXED, __HIP_MEMORY_SCOPE_AGENT);
;                 if (m & 1) asm volatile("" ::: "memory");
;             }
.LBB0_632:
	s_or_b64 exec, exec, s[26:27]
	v_add_u32_e32 v32, 0xa0, v136
	s_waitcnt lgkmcnt(0)
	v_ashrrev_i32_e32 v33, 31, v32
	v_lshlrev_b64 v[34:35], 12, v[32:33]
	v_lshl_add_u64 v[34:35], s[10:11], 0, v[34:35]
	v_lshl_add_u64 v[38:39], v[134:135], 1, v[34:35]
	s_nop 1
	s_waitcnt vmcnt(14)
	s_nop 0
	v_lshlrev_b32_e32 v40, 16, v154
	v_and_b32_e32 v41, 0xffff0000, v154
	v_lshlrev_b32_e32 v34, 16, v155
	v_and_b32_e32 v35, 0xffff0000, v155
	v_lshlrev_b32_e32 v42, 16, v156
	v_and_b32_e32 v43, 0xffff0000, v156
	v_lshlrev_b32_e32 v36, 16, v157
	v_and_b32_e32 v37, 0xffff0000, v157
	v_pk_add_f32 v[34:35], v[30:31], v[34:35]
	v_pk_add_f32 v[40:41], v[28:29], v[40:41]
	v_pk_add_f32 v[36:37], v[26:27], v[36:37]
	v_pk_add_f32 v[42:43], v[24:25], v[42:43]
	v_cvt_pk_bf16_f32 v24, v40, v41
	v_cvt_pk_bf16_f32 v25, v34, v35
	v_mul_f32_e32 v41, v41, v41
	v_cvt_pk_bf16_f32 v26, v42, v43
	v_cvt_pk_bf16_f32 v27, v36, v37
	s_nop 1
	s_waitcnt vmcnt(13)
	v_mul_f32_e32 v35, v35, v35
	v_mul_f32_e32 v43, v43, v43
	v_fmac_f32_e32 v41, v40, v40
	v_fmac_f32_e32 v35, v34, v34
	v_mul_f32_e32 v37, v37, v37
	v_fmac_f32_e32 v43, v42, v42
	v_add_f32_e32 v34, v41, v35
	v_fmac_f32_e32 v37, v36, v36
	v_add_f32_e32 v34, v43, v34
	v_add_f32_e32 v40, v37, v34
	global_store_dwordx4 v[38:39], v[24:27], off
	s_nop 0
	v_lshlrev_b32_e32 v34, 16, v158
	v_and_b32_e32 v35, 0xffff0000, v158
	v_lshlrev_b32_e32 v28, 16, v159
	v_and_b32_e32 v29, 0xffff0000, v159
	v_lshlrev_b32_e32 v36, 16, v160
	v_and_b32_e32 v37, 0xffff0000, v160
	v_lshlrev_b32_e32 v30, 16, v161
	v_and_b32_e32 v31, 0xffff0000, v161
	v_pk_add_f32 v[22:23], v[22:23], v[28:29]
	v_pk_add_f32 v[20:21], v[20:21], v[34:35]
	v_pk_add_f32 v[28:29], v[18:19], v[30:31]
	v_pk_add_f32 v[30:31], v[16:17], v[36:37]
	v_mul_f32_e32 v16, v21, v21
	v_mul_f32_e32 v17, v23, v23
	v_mul_f32_e32 v18, v31, v31
	v_fmac_f32_e32 v16, v20, v20
	v_fmac_f32_e32 v17, v22, v22
	v_mul_f32_e32 v19, v29, v29
	v_fmac_f32_e32 v18, v30, v30
	v_add_f32_e32 v16, v16, v17
	v_add_f32_e32 v16, v18, v16
	v_fmac_f32_e32 v19, v28, v28
	v_add_f32_e32 v16, v19, v16
	v_add_f32_e32 v16, v40, v16
	ds_bpermute_b32 v17, v114, v16
	v_cvt_pk_bf16_f32 v18, v20, v21
	v_cvt_pk_bf16_f32 v19, v22, v23
	v_cvt_pk_bf16_f32 v20, v30, v31
	v_cvt_pk_bf16_f32 v21, v28, v29
	s_waitcnt lgkmcnt(0)
	v_add_f32_e32 v16, v16, v17
	ds_bpermute_b32 v17, v115, v16
	global_store_dwordx4 v[38:39], v[18:21], off offset:64
	s_and_saveexec_b64 s[26:27], s[2:3]
	s_cbranch_execz .LBB0_634
	v_lshl_add_u64 v[18:19], v[32:33], 2, s[12:13]
	s_waitcnt lgkmcnt(0)
	v_add_f32_e32 v16, v16, v17
	global_atomic_add_f32 v[18:19], v16, off
.LBB0_634:
	s_or_b64 exec, exec, s[26:27]
	v_add_u32_e32 v16, 0xb0, v136
	s_waitcnt lgkmcnt(0)
	v_ashrrev_i32_e32 v17, 31, v16
	v_lshlrev_b64 v[18:19], 12, v[16:17]
	v_lshl_add_u64 v[18:19], s[10:11], 0, v[18:19]
	v_lshl_add_u64 v[22:23], v[134:135], 1, v[18:19]
	s_nop 1
	s_waitcnt vmcnt(12)
	s_nop 0
	v_lshlrev_b32_e32 v24, 16, v162
	v_and_b32_e32 v25, 0xffff0000, v162
	v_lshlrev_b32_e32 v18, 16, v163
	v_and_b32_e32 v19, 0xffff0000, v163
	v_lshlrev_b32_e32 v26, 16, v164
	v_and_b32_e32 v27, 0xffff0000, v164
	v_lshlrev_b32_e32 v20, 16, v165
	v_and_b32_e32 v21, 0xffff0000, v165
	v_pk_add_f32 v[18:19], v[14:15], v[18:19]
	v_pk_add_f32 v[24:25], v[12:13], v[24:25]
	v_pk_add_f32 v[20:21], v[10:11], v[20:21]
	v_pk_add_f32 v[26:27], v[8:9], v[26:27]
	v_cvt_pk_bf16_f32 v8, v24, v25
	v_cvt_pk_bf16_f32 v9, v18, v19
	v_mul_f32_e32 v25, v25, v25
	v_cvt_pk_bf16_f32 v10, v26, v27
	v_cvt_pk_bf16_f32 v11, v20, v21
	s_nop 1
	s_waitcnt vmcnt(11)
	v_mul_f32_e32 v19, v19, v19
	v_mul_f32_e32 v27, v27, v27
	v_fmac_f32_e32 v25, v24, v24
	v_fmac_f32_e32 v19, v18, v18
	v_mul_f32_e32 v21, v21, v21
	v_fmac_f32_e32 v27, v26, v26
	v_add_f32_e32 v18, v25, v19
	v_fmac_f32_e32 v21, v20, v20
	v_add_f32_e32 v18, v27, v18
	v_add_f32_e32 v24, v21, v18
	global_store_dwordx4 v[22:23], v[8:11], off
	s_nop 0
	v_lshlrev_b32_e32 v18, 16, v166
	v_and_b32_e32 v19, 0xffff0000, v166
	v_lshlrev_b32_e32 v12, 16, v167
	v_and_b32_e32 v13, 0xffff0000, v167
	v_lshlrev_b32_e32 v20, 16, v168
	v_and_b32_e32 v21, 0xffff0000, v168
	v_lshlrev_b32_e32 v14, 16, v169
	v_and_b32_e32 v15, 0xffff0000, v169
	v_pk_add_f32 v[6:7], v[6:7], v[12:13]
	v_pk_add_f32 v[4:5], v[4:5], v[18:19]
	v_pk_add_f32 v[12:13], v[2:3], v[14:15]
	v_pk_add_f32 v[14:15], v[0:1], v[20:21]
	v_mul_f32_e32 v0, v5, v5
	v_mul_f32_e32 v1, v7, v7
	v_mul_f32_e32 v2, v15, v15
	v_fmac_f32_e32 v0, v4, v4
	v_fmac_f32_e32 v1, v6, v6
	v_mul_f32_e32 v3, v13, v13
	v_fmac_f32_e32 v2, v14, v14
	v_add_f32_e32 v0, v0, v1
	v_add_f32_e32 v0, v2, v0
	v_fmac_f32_e32 v3, v12, v12
	v_add_f32_e32 v0, v3, v0
	v_add_f32_e32 v0, v24, v0
	ds_bpermute_b32 v1, v114, v0
	v_cvt_pk_bf16_f32 v2, v4, v5
	v_cvt_pk_bf16_f32 v3, v6, v7
	v_cvt_pk_bf16_f32 v4, v14, v15
	v_cvt_pk_bf16_f32 v5, v12, v13
	s_waitcnt lgkmcnt(0)
	v_add_f32_e32 v0, v0, v1
	ds_bpermute_b32 v1, v115, v0
	global_store_dwordx4 v[22:23], v[2:5], off offset:64
	s_and_saveexec_b64 s[26:27], s[2:3]
	s_cbranch_execz .LBB0_636
	v_lshl_add_u64 v[2:3], v[16:17], 2, s[12:13]
	s_waitcnt lgkmcnt(0)
	v_add_f32_e32 v0, v0, v1
	global_atomic_add_f32 v[2:3], v0, off

; __device__ __forceinline__ u32x4 pack8(f32x4 a, f32x4 b) { u32x4 w; w.x = cvt_pk_bf16(a[0], a[1]); w.y = cvt_pk_bf16(a[2], a[3]); w.z = cvt_pk_bf16(b[0], b[1]); w.w = cvt_pk_bf16(b[2], b[3]); return w; }
;     __device__ __forceinline__ void operator()(const f32x4 (&acc)[2][2][4][2], const Unit& u, int wr, int wc, int fr, int fq) const {
;     ...
;         for (int ai = 0; ai < 2; ++ai)
; #pragma unroll
;             for (int m = 0; m < 4; ++m) {
;                 const int row = row0 + ai * HALF + m * 16; const size_t off = (size_t)row * 2048 + col;
;                 float s = 0.f;
; #pragma unroll
;                 for (int bj = 0; bj < 2; ++bj) {
;                     f32x4 b0, b1;
;                     if (BASE_F32) { const float* bp = (const float*)base + off + bj * 32; b0 = *(const f32x4*)bp; b1 = *(const f32x4*)(bp + 4); }
;                     else { const u32x4 w = *(const u32x4*)((const bf16_t*)base + off + bj * 32);
;                         b0 = (f32x4){__uint_as_float(w.x << 16), __uint_as_float(w.x & 0xffff0000u), __uint_as_float(w.y << 16), __uint_as_float(w.y & 0xffff0000u)};
;                         b1 = (f32x4){__uint_as_float(w.z << 16), __uint_as_float(w.z & 0xffff0000u), __uint_as_float(w.w << 16), __uint_as_float(w.w & 0xffff0000u)}; }
;                     const f32x4 h0 = b0 + acc[ai][bj][m][0], h1 = b1 + acc[ai][bj][m][1];
;                     s += (h0[0] * h0[0] + h0[1] * h0[1]) + (h0[2] * h0[2] + h0[3] * h0[3]) + (h1[0] * h1[0] + h1[1] * h1[1]) + (h1[2] * h1[2] + h1[3] * h1[3]);
;                     *(u32x4*)(H + off + bj * 32) = pack8(h0, h1);
;                 }
;                 s += __shfl_xor(s, 16); s += __shfl_xor(s, 32);
;                 if (fq == 0) __hip_atomic_fetch_add(ss + row, s, __ATOMIC_RELAXED, __HIP_MEMORY_SCOPE_AGENT);
;                 if (m & 1) asm volatile("" ::: "memory");
;             }
.LBB0_798:
	v_lshl_add_u32 v138, s24, 8, v141
	v_ashrrev_i32_e32 v139, 31, v138
	v_lshl_or_b32 v136, s26, 8, v143
	v_lshlrev_b64 v[134:135], 12, v[138:139]
	v_ashrrev_i32_e32 v137, 31, v136
	v_lshl_add_u64 v[134:135], s[8:9], 0, v[134:135]
	v_lshl_add_u64 v[134:135], v[136:137], 1, v[134:135]
	v_mov_b32_e32 v220, v138
	v_ashrrev_i32_e32 v221, 31, v220
	v_lshlrev_b64 v[220:221], 12, v[220:221]
	v_lshl_add_u64 v[220:221], s[8:9], 0, v[220:221]
	v_lshl_add_u64 v[220:221], v[136:137], 1, v[220:221]
	global_load_dwordx4 v[154:157], v[220:221], off
	global_load_dwordx4 v[158:161], v[220:221], off offset:64
	v_add_u32_e32 v220, 0x10, v138
	v_ashrrev_i32_e32 v221, 31, v220
	v_lshlrev_b64 v[220:221], 12, v[220:221]
	v_lshl_add_u64 v[220:221], s[8:9], 0, v[220:221]
	v_lshl_add_u64 v[220:221], v[136:137], 1, v[220:221]
	global_load_dwordx4 v[162:165], v[220:221], off
	global_load_dwordx4 v[166:169], v[220:221], off offset:64
	v_add_u32_e32 v220, 0x20, v138
	v_ashrrev_i32_e32 v221, 31, v220
	v_lshlrev_b64 v[220:221], 12, v[220:221]
	v_lshl_add_u64 v[220:221], s[8:9], 0, v[220:221]
	v_lshl_add_u64 v[220:221], v[136:137], 1, v[220:221]
	global_load_dwordx4 v[178:181], v[220:221], off
	global_load_dwordx4 v[182:185], v[220:221], off offset:64
	v_add_u32_e32 v220, 0x30, v138
	v_ashrrev_i32_e32 v221, 31, v220
	v_lshlrev_b64 v[220:221], 12, v[220:221]
	v_lshl_add_u64 v[220:221], s[8:9], 0, v[220:221]
	v_lshl_add_u64 v[220:221], v[136:137], 1, v[220:221]
	global_load_dwordx4 v[186:189], v[220:221], off
	global_load_dwordx4 v[190:193], v[220:221], off offset:64
	v_add_u32_e32 v220, 0x80, v138
	v_ashrrev_i32_e32 v221, 31, v220
	v_lshlrev_b64 v[220:221], 12, v[220:221]
	v_lshl_add_u64 v[220:221], s[8:9], 0, v[220:221]
	v_lshl_add_u64 v[220:221], v[136:137], 1, v[220:221]
	global_load_dwordx4 v[194:197], v[220:221], off
	global_load_dwordx4 v[198:201], v[220:221], off offset:64
	v_add_u32_e32 v220, 0x90, v138
	v_ashrrev_i32_e32 v221, 31, v220
	v_lshlrev_b64 v[220:221], 12, v[220:221]
	v_lshl_add_u64 v[220:221], s[8:9], 0, v[220:221]
	v_lshl_add_u64 v[220:221], v[136:137], 1, v[220:221]
	global_load_dwordx4 v[212:215], v[220:221], off
	global_load_dwordx4 v[216:219], v[220:221], off offset:64
	s_nop 1
	s_waitcnt vmcnt(11)
	s_nop 0
	v_lshlrev_b32_e32 v150, 16, v154
	v_and_b32_e32 v151, 0xffff0000, v154
	v_lshlrev_b32_e32 v146, 16, v155
	v_and_b32_e32 v147, 0xffff0000, v155
	v_lshlrev_b32_e32 v152, 16, v156
	v_and_b32_e32 v153, 0xffff0000, v156
	v_lshlrev_b32_e32 v148, 16, v157
	v_and_b32_e32 v149, 0xffff0000, v157
	v_pk_add_f32 v[126:127], v[126:127], v[146:147]
	v_pk_add_f32 v[124:125], v[124:125], v[150:151]
	v_pk_add_f32 v[146:147], v[122:123], v[148:149]
	v_pk_add_f32 v[122:123], v[120:121], v[152:153]
	v_mul_f32_e32 v120, v125, v125
	v_mul_f32_e32 v121, v127, v127
	v_fmac_f32_e32 v120, v124, v124
	v_fmac_f32_e32 v121, v126, v126
	v_add_f32_e32 v120, v120, v121
	v_mul_f32_e32 v121, v123, v123
	v_fmac_f32_e32 v121, v122, v122
	v_add_f32_e32 v120, v121, v120
	v_mul_f32_e32 v121, v147, v147
	v_fmac_f32_e32 v121, v146, v146
	v_add_f32_e32 v145, v121, v120
	v_cvt_pk_bf16_f32 v120, v124, v125
	v_cvt_pk_bf16_f32 v121, v126, v127
	v_cvt_pk_bf16_f32 v122, v122, v123
	v_cvt_pk_bf16_f32 v123, v146, v147
	global_store_dwordx4 v[134:135], v[120:123], off
	s_nop 1
	s_waitcnt vmcnt(11)
	s_nop 0
	v_lshlrev_b32_e32 v124, 16, v158
	v_and_b32_e32 v125, 0xffff0000, v158
	v_lshlrev_b32_e32 v120, 16, v159
	v_and_b32_e32 v121, 0xffff0000, v159
	v_lshlrev_b32_e32 v126, 16, v160
	v_and_b32_e32 v127, 0xffff0000, v160
	v_lshlrev_b32_e32 v122, 16, v161
	v_and_b32_e32 v123, 0xffff0000, v161
	v_add_u32_e32 v220, 0xa0, v138
	v_ashrrev_i32_e32 v221, 31, v220
	v_lshlrev_b64 v[220:221], 12, v[220:221]
	v_lshl_add_u64 v[220:221], s[8:9], 0, v[220:221]
	v_lshl_add_u64 v[220:221], v[136:137], 1, v[220:221]
	global_load_dwordx4 v[154:157], v[220:221], off
	global_load_dwordx4 v[158:161], v[220:221], off offset:64
	v_pk_add_f32 v[118:119], v[118:119], v[120:121]
	v_pk_add_f32 v[116:117], v[116:117], v[124:125]
	v_pk_add_f32 v[120:121], v[114:115], v[122:123]
	v_pk_add_f32 v[114:115], v[112:113], v[126:127]
	v_mul_f32_e32 v112, v117, v117
	v_mul_f32_e32 v113, v119, v119
	v_fmac_f32_e32 v112, v116, v116
	v_fmac_f32_e32 v113, v118, v118
	v_add_f32_e32 v112, v112, v113
	v_mul_f32_e32 v113, v115, v115
	v_fmac_f32_e32 v113, v114, v114
	v_add_f32_e32 v112, v113, v112
	v_mul_f32_e32 v113, v121, v121
	v_fmac_f32_e32 v113, v120, v120
	v_add_f32_e32 v112, v113, v112
	v_add_f32_e32 v122, v145, v112
	v_cvt_pk_bf16_f32 v112, v116, v117
	v_cvt_pk_bf16_f32 v113, v118, v119
	v_cvt_pk_bf16_f32 v114, v114, v115
	v_cvt_pk_bf16_f32 v115, v120, v121
	global_store_dwordx4 v[134:135], v[112:115], off offset:64
	s_nop 1
	v_and_b32_e32 v113, 64, v209
	v_xor_b32_e32 v112, 16, v209
	v_add_u32_e32 v113, 64, v113
	v_cmp_lt_i32_e32 vcc, v112, v113
	s_nop 1
	v_cndmask_b32_e32 v112, v209, v112, vcc
	v_lshlrev_b32_e32 v114, 2, v112
	ds_bpermute_b32 v112, v114, v122
	s_waitcnt lgkmcnt(0)
	v_add_f32_e32 v116, v122, v112
	v_xor_b32_e32 v112, 32, v209
	v_cmp_lt_i32_e32 vcc, v112, v113
	s_nop 1
	v_cndmask_b32_e32 v112, v209, v112, vcc
	v_lshlrev_b32_e32 v115, 2, v112
	ds_bpermute_b32 v117, v115, v116
	v_lshl_add_u64 v[112:113], v[138:139], 2, s[10:11]
	s_and_saveexec_b64 s[24:25], s[2:3]
	s_cbranch_execz .LBB0_800
	s_waitcnt lgkmcnt(0)
	v_add_f32_e32 v116, v116, v117
	global_atomic_add_f32 v[112:113], v116, off
; __device__ __forceinline__ u32x4 pack8(f32x4 a, f32x4 b) { u32x4 w; w.x = cvt_pk_bf16(a[0], a[1]); w.y = cvt_pk_bf16(a[2], a[3]); w.z = cvt_pk_bf16(b[0], b[1]); w.w = cvt_pk_bf16(b[2], b[3]); return w; }
;     __device__ __forceinline__ void operator()(const f32x4 (&acc)[2][2][4][2], const Unit& u, int wr, int wc, int fr, int fq) const {
;     ...
;         for (int ai = 0; ai < 2; ++ai)
; #pragma unroll
;             for (int m = 0; m < 4; ++m) {
;                 const int row = row0 + ai * HALF + m * 16; const size_t off = (size_t)row * 2048 + col;
;                 float s = 0.f;
; #pragma unroll
;                 for (int bj = 0; bj < 2; ++bj) {
;                     f32x4 b0, b1;
;                     if (BASE_F32) { const float* bp = (const float*)base + off + bj * 32; b0 = *(const f32x4*)bp; b1 = *(const f32x4*)(bp + 4); }
;                     else { const u32x4 w = *(const u32x4*)((const bf16_t*)base + off + bj * 32);
;                         b0 = (f32x4){__uint_as_float(w.x << 16), __uint_as_float(w.x & 0xffff0000u), __uint_as_float(w.y << 16), __uint_as_float(w.y & 0xffff0000u)};
;                         b1 = (f32x4){__uint_as_float(w.z << 16), __uint_as_float(w.z & 0xffff0000u), __uint_as_float(w.w << 16), __uint_as_float(w.w & 0xffff0000u)}; }
;                     const f32x4 h0 = b0 + acc[ai][bj][m][0], h1 = b1 + acc[ai][bj][m][1];
;                     s += (h0[0] * h0[0] + h0[1] * h0[1]) + (h0[2] * h0[2] + h0[3] * h0[3]) + (h1[0] * h1[0] + h1[1] * h1[1]) + (h1[2] * h1[2] + h1[3] * h1[3]);
;                     *(u32x4*)(H + off + bj * 32) = pack8(h0, h1);
;                 }
;                 s += __shfl_xor(s, 16); s += __shfl_xor(s, 32);
;                 if (fq == 0) __hip_atomic_fetch_add(ss + row, s, __ATOMIC_RELAXED, __HIP_MEMORY_SCOPE_AGENT);
;                 if (m & 1) asm volatile("" ::: "memory");
;             }
.LBB0_800:
	s_or_b64 exec, exec, s[24:25]
	v_or_b32_e32 v116, 16, v138
	s_waitcnt lgkmcnt(0)
	v_ashrrev_i32_e32 v117, 31, v116
	v_lshlrev_b64 v[116:117], 12, v[116:117]
	v_lshl_add_u64 v[116:117], s[8:9], 0, v[116:117]
	v_lshl_add_u64 v[120:121], v[136:137], 1, v[116:117]
	s_nop 1
	s_waitcnt vmcnt(13)
	s_nop 0
	v_lshlrev_b32_e32 v122, 16, v162
	v_and_b32_e32 v123, 0xffff0000, v162
	v_lshlrev_b32_e32 v116, 16, v163
	v_and_b32_e32 v117, 0xffff0000, v163
	v_lshlrev_b32_e32 v124, 16, v164
	v_and_b32_e32 v125, 0xffff0000, v164
	v_lshlrev_b32_e32 v118, 16, v165
	v_and_b32_e32 v119, 0xffff0000, v165
	v_pk_add_f32 v[116:117], v[110:111], v[116:117]
	v_pk_add_f32 v[122:123], v[108:109], v[122:123]
	v_pk_add_f32 v[118:119], v[106:107], v[118:119]
	v_pk_add_f32 v[124:125], v[104:105], v[124:125]
	v_cvt_pk_bf16_f32 v104, v122, v123
	v_cvt_pk_bf16_f32 v105, v116, v117
	v_mul_f32_e32 v123, v123, v123
	v_cvt_pk_bf16_f32 v106, v124, v125
	v_cvt_pk_bf16_f32 v107, v118, v119
	s_nop 1
	s_waitcnt vmcnt(12)
	v_mul_f32_e32 v117, v117, v117
	v_mul_f32_e32 v125, v125, v125
	v_fmac_f32_e32 v123, v122, v122
	v_fmac_f32_e32 v117, v116, v116
	v_mul_f32_e32 v119, v119, v119
	v_fmac_f32_e32 v125, v124, v124
	v_add_f32_e32 v116, v123, v117
	v_fmac_f32_e32 v119, v118, v118
	v_add_f32_e32 v116, v125, v116
	v_add_f32_e32 v122, v119, v116
	global_store_dwordx4 v[120:121], v[104:107], off
	s_nop 0
	v_lshlrev_b32_e32 v116, 16, v166
	v_and_b32_e32 v117, 0xffff0000, v166
	v_lshlrev_b32_e32 v108, 16, v167
	v_and_b32_e32 v109, 0xffff0000, v167
	v_lshlrev_b32_e32 v118, 16, v168
	v_and_b32_e32 v119, 0xffff0000, v168
	v_lshlrev_b32_e32 v110, 16, v169
	v_and_b32_e32 v111, 0xffff0000, v169
	v_add_u32_e32 v220, 0xb0, v138
	v_ashrrev_i32_e32 v221, 31, v220
	v_lshlrev_b64 v[220:221], 12, v[220:221]
	v_lshl_add_u64 v[220:221], s[8:9], 0, v[220:221]
	v_lshl_add_u64 v[220:221], v[136:137], 1, v[220:221]
	global_load_dwordx4 v[162:165], v[220:221], off
	global_load_dwordx4 v[166:169], v[220:221], off offset:64
	v_pk_add_f32 v[102:103], v[102:103], v[108:109]
	v_pk_add_f32 v[100:101], v[100:101], v[116:117]
	v_pk_add_f32 v[108:109], v[98:99], v[110:111]
	v_pk_add_f32 v[110:111], v[96:97], v[118:119]
	v_mul_f32_e32 v96, v101, v101
	v_mul_f32_e32 v97, v103, v103
	v_mul_f32_e32 v98, v111, v111
	v_fmac_f32_e32 v96, v100, v100
	v_fmac_f32_e32 v97, v102, v102
	v_mul_f32_e32 v99, v109, v109
	v_fmac_f32_e32 v98, v110, v110
	v_add_f32_e32 v96, v96, v97
	v_add_f32_e32 v96, v98, v96
	v_fmac_f32_e32 v99, v108, v108
	v_add_f32_e32 v96, v99, v96
	v_add_f32_e32 v96, v122, v96
	ds_bpermute_b32 v97, v114, v96
	v_cvt_pk_bf16_f32 v98, v100, v101
	v_cvt_pk_bf16_f32 v99, v102, v103
	v_cvt_pk_bf16_f32 v100, v110, v111
	v_cvt_pk_bf16_f32 v101, v108, v109
	s_waitcnt lgkmcnt(0)
	v_add_f32_e32 v96, v96, v97
	ds_bpermute_b32 v97, v115, v96
	global_store_dwordx4 v[120:121], v[98:101], off offset:64
	s_and_saveexec_b64 s[24:25], s[2:3]
	s_cbranch_execz .LBB0_802
	s_waitcnt lgkmcnt(0)
	v_add_f32_e32 v96, v96, v97
	global_atomic_add_f32 v[112:113], v96, off offset:64
.LBB0_802:
	s_or_b64 exec, exec, s[24:25]
	v_or_b32_e32 v96, 32, v138
	s_waitcnt lgkmcnt(0)
	v_ashrrev_i32_e32 v97, 31, v96
	v_lshlrev_b64 v[96:97], 12, v[96:97]
	v_lshl_add_u64 v[96:97], s[8:9], 0, v[96:97]
	v_lshl_add_u64 v[100:101], v[136:137], 1, v[96:97]
	s_nop 1
	s_waitcnt vmcnt(15)
	s_nop 0
	v_lshlrev_b32_e32 v102, 16, v178
	v_and_b32_e32 v103, 0xffff0000, v178
	v_lshlrev_b32_e32 v96, 16, v179
	v_and_b32_e32 v97, 0xffff0000, v179
	v_lshlrev_b32_e32 v104, 16, v180
	v_and_b32_e32 v105, 0xffff0000, v180
	v_lshlrev_b32_e32 v98, 16, v181
	v_and_b32_e32 v99, 0xffff0000, v181
	v_pk_add_f32 v[96:97], v[94:95], v[96:97]
	v_pk_add_f32 v[102:103], v[92:93], v[102:103]
	v_pk_add_f32 v[98:99], v[90:91], v[98:99]
	v_pk_add_f32 v[104:105], v[88:89], v[104:105]
	v_cvt_pk_bf16_f32 v88, v102, v103
	v_cvt_pk_bf16_f32 v89, v96, v97
	v_mul_f32_e32 v103, v103, v103
	v_cvt_pk_bf16_f32 v90, v104, v105
	v_cvt_pk_bf16_f32 v91, v98, v99
	s_nop 1
	s_waitcnt vmcnt(14)
	v_mul_f32_e32 v97, v97, v97
	v_mul_f32_e32 v105, v105, v105
	v_fmac_f32_e32 v103, v102, v102
	v_fmac_f32_e32 v97, v96, v96
	v_mul_f32_e32 v99, v99, v99
	v_fmac_f32_e32 v105, v104, v104
	v_add_f32_e32 v96, v103, v97
	v_fmac_f32_e32 v99, v98, v98
	v_add_f32_e32 v96, v105, v96
	v_add_f32_e32 v102, v99, v96
	global_store_dwordx4 v[100:101], v[88:91], off
	s_nop 0
	v_lshlrev_b32_e32 v96, 16, v182
	v_and_b32_e32 v97, 0xffff0000, v182
	v_lshlrev_b32_e32 v92, 16, v183
	v_and_b32_e32 v93, 0xffff0000, v183
	v_lshlrev_b32_e32 v98, 16, v184
	v_and_b32_e32 v99, 0xffff0000, v184
	v_lshlrev_b32_e32 v94, 16, v185
	v_and_b32_e32 v95, 0xffff0000, v185
	v_pk_add_f32 v[86:87], v[86:87], v[92:93]
	v_pk_add_f32 v[84:85], v[84:85], v[96:97]
	v_pk_add_f32 v[92:93], v[82:83], v[94:95]
	v_pk_add_f32 v[94:95], v[80:81], v[98:99]
	v_mul_f32_e32 v80, v85, v85
	v_mul_f32_e32 v81, v87, v87
	v_mul_f32_e32 v82, v95, v95
	v_fmac_f32_e32 v80, v84, v84
	v_fmac_f32_e32 v81, v86, v86
	v_mul_f32_e32 v83, v93, v93
	v_fmac_f32_e32 v82, v94, v94
	v_add_f32_e32 v80, v80, v81
	v_add_f32_e32 v80, v82, v80
	v_fmac_f32_e32 v83, v92, v92
	v_add_f32_e32 v80, v83, v80
	v_add_f32_e32 v80, v102, v80
	ds_bpermute_b32 v81, v114, v80
	v_cvt_pk_bf16_f32 v82, v84, v85
	v_cvt_pk_bf16_f32 v83, v86, v87
	v_cvt_pk_bf16_f32 v84, v94, v95
	v_cvt_pk_bf16_f32 v85, v92, v93
	s_waitcnt lgkmcnt(0)
	v_add_f32_e32 v80, v80, v81
	ds_bpermute_b32 v81, v115, v80
	global_store_dwordx4 v[100:101], v[82:85], off offset:64
	s_and_saveexec_b64 s[24:25], s[2:3]
	s_cbranch_execz .LBB0_804
	s_waitcnt lgkmcnt(0)
	v_add_f32_e32 v80, v80, v81
	global_atomic_add_f32 v[112:113], v80, off offset:128
; __device__ __forceinline__ u32x4 pack8(f32x4 a, f32x4 b) { u32x4 w; w.x = cvt_pk_bf16(a[0], a[1]); w.y = cvt_pk_bf16(a[2], a[3]); w.z = cvt_pk_bf16(b[0], b[1]); w.w = cvt_pk_bf16(b[2], b[3]); return w; }
;     __device__ __forceinline__ void operator()(const f32x4 (&acc)[2][2][4][2], const Unit& u, int wr, int wc, int fr, int fq) const {
;     ...
;         for (int ai = 0; ai < 2; ++ai)
; #pragma unroll
;             for (int m = 0; m < 4; ++m) {
;                 const int row = row0 + ai * HALF + m * 16; const size_t off = (size_t)row * 2048 + col;
;                 float s = 0.f;
; #pragma unroll
;                 for (int bj = 0; bj < 2; ++bj) {
;                     f32x4 b0, b1;
;                     if (BASE_F32) { const float* bp = (const float*)base + off + bj * 32; b0 = *(const f32x4*)bp; b1 = *(const f32x4*)(bp + 4); }
;                     else { const u32x4 w = *(const u32x4*)((const bf16_t*)base + off + bj * 32);
;                         b0 = (f32x4){__uint_as_float(w.x << 16), __uint_as_float(w.x & 0xffff0000u), __uint_as_float(w.y << 16), __uint_as_float(w.y & 0xffff0000u)};
;                         b1 = (f32x4){__uint_as_float(w.z << 16), __uint_as_float(w.z & 0xffff0000u), __uint_as_float(w.w << 16), __uint_as_float(w.w & 0xffff0000u)}; }
;                     const f32x4 h0 = b0 + acc[ai][bj][m][0], h1 = b1 + acc[ai][bj][m][1];
;                     s += (h0[0] * h0[0] + h0[1] * h0[1]) + (h0[2] * h0[2] + h0[3] * h0[3]) + (h1[0] * h1[0] + h1[1] * h1[1]) + (h1[2] * h1[2] + h1[3] * h1[3]);
;                     *(u32x4*)(H + off + bj * 32) = pack8(h0, h1);
;                 }
;                 s += __shfl_xor(s, 16); s += __shfl_xor(s, 32);
;                 if (fq == 0) __hip_atomic_fetch_add(ss + row, s, __ATOMIC_RELAXED, __HIP_MEMORY_SCOPE_AGENT);
;                 if (m & 1) asm volatile("" ::: "memory");
;             }
.LBB0_804:
	s_or_b64 exec, exec, s[24:25]
	v_or_b32_e32 v80, 48, v138
	s_waitcnt lgkmcnt(0)
	v_ashrrev_i32_e32 v81, 31, v80
	v_lshlrev_b64 v[80:81], 12, v[80:81]
	v_lshl_add_u64 v[80:81], s[8:9], 0, v[80:81]
	v_lshl_add_u64 v[84:85], v[136:137], 1, v[80:81]
	s_nop 1
	s_waitcnt vmcnt(15)
	s_nop 0
	v_lshlrev_b32_e32 v86, 16, v186
	v_and_b32_e32 v87, 0xffff0000, v186
	v_lshlrev_b32_e32 v80, 16, v187
	v_and_b32_e32 v81, 0xffff0000, v187
	v_lshlrev_b32_e32 v88, 16, v188
	v_and_b32_e32 v89, 0xffff0000, v188
	v_lshlrev_b32_e32 v82, 16, v189
	v_and_b32_e32 v83, 0xffff0000, v189
	v_pk_add_f32 v[80:81], v[78:79], v[80:81]
	v_pk_add_f32 v[86:87], v[76:77], v[86:87]
	v_pk_add_f32 v[82:83], v[74:75], v[82:83]
	v_pk_add_f32 v[88:89], v[72:73], v[88:89]
	v_cvt_pk_bf16_f32 v72, v86, v87
	v_cvt_pk_bf16_f32 v73, v80, v81
	v_mul_f32_e32 v87, v87, v87
	v_cvt_pk_bf16_f32 v74, v88, v89
	v_cvt_pk_bf16_f32 v75, v82, v83
	s_nop 1
	s_waitcnt vmcnt(14)
	v_mul_f32_e32 v81, v81, v81
	v_mul_f32_e32 v89, v89, v89
	v_fmac_f32_e32 v87, v86, v86
	v_fmac_f32_e32 v81, v80, v80
	v_mul_f32_e32 v83, v83, v83
	v_fmac_f32_e32 v89, v88, v88
	v_add_f32_e32 v80, v87, v81
	v_fmac_f32_e32 v83, v82, v82
	v_add_f32_e32 v80, v89, v80
	v_add_f32_e32 v86, v83, v80
	global_store_dwordx4 v[84:85], v[72:75], off
	s_nop 0
	v_lshlrev_b32_e32 v80, 16, v190
	v_and_b32_e32 v81, 0xffff0000, v190
	v_lshlrev_b32_e32 v76, 16, v191
	v_and_b32_e32 v77, 0xffff0000, v191
	v_lshlrev_b32_e32 v82, 16, v192
	v_and_b32_e32 v83, 0xffff0000, v192
	v_lshlrev_b32_e32 v78, 16, v193
	v_and_b32_e32 v79, 0xffff0000, v193
	v_pk_add_f32 v[70:71], v[70:71], v[76:77]
	v_pk_add_f32 v[68:69], v[68:69], v[80:81]
	v_pk_add_f32 v[76:77], v[66:67], v[78:79]
	v_pk_add_f32 v[78:79], v[64:65], v[82:83]
	v_mul_f32_e32 v64, v69, v69
	v_mul_f32_e32 v65, v71, v71
	v_mul_f32_e32 v66, v79, v79
	v_fmac_f32_e32 v64, v68, v68
	v_fmac_f32_e32 v65, v70, v70
	v_mul_f32_e32 v67, v77, v77
	v_fmac_f32_e32 v66, v78, v78
	v_add_f32_e32 v64, v64, v65
	v_add_f32_e32 v64, v66, v64
	v_fmac_f32_e32 v67, v76, v76
	v_add_f32_e32 v64, v67, v64
	v_add_f32_e32 v64, v86, v64
	ds_bpermute_b32 v65, v114, v64
	v_cvt_pk_bf16_f32 v66, v68, v69
	v_cvt_pk_bf16_f32 v67, v70, v71
	v_cvt_pk_bf16_f32 v68, v78, v79
	v_cvt_pk_bf16_f32 v69, v76, v77
	s_waitcnt lgkmcnt(0)
	v_add_f32_e32 v64, v64, v65
	ds_bpermute_b32 v65, v115, v64
	global_store_dwordx4 v[84:85], v[66:69], off offset:64
	s_and_saveexec_b64 s[24:25], s[2:3]
	s_cbranch_execz .LBB0_806
	s_waitcnt lgkmcnt(0)
	v_add_f32_e32 v64, v64, v65
	global_atomic_add_f32 v[112:113], v64, off offset:192
.LBB0_806:
	s_or_b64 exec, exec, s[24:25]
	v_add_co_u32_e32 v68, vcc, 0x80000, v134
	s_mov_b64 s[24:25], 0x80000
	s_nop 0
	v_addc_co_u32_e32 v69, vcc, 0, v135, vcc
	s_waitcnt lgkmcnt(0)
	s_nop 1
	s_waitcnt vmcnt(15)
	v_lshl_add_u64 v[70:71], v[134:135], 0, s[24:25]
	s_nop 0
	v_lshlrev_b32_e32 v72, 16, v194
	v_and_b32_e32 v73, 0xffff0000, v194
	v_lshlrev_b32_e32 v64, 16, v195
	v_and_b32_e32 v65, 0xffff0000, v195
	v_lshlrev_b32_e32 v74, 16, v196
	v_and_b32_e32 v75, 0xffff0000, v196
	v_lshlrev_b32_e32 v66, 16, v197
	v_and_b32_e32 v67, 0xffff0000, v197
	v_pk_add_f32 v[64:65], v[62:63], v[64:65]
	v_pk_add_f32 v[72:73], v[60:61], v[72:73]
	v_pk_add_f32 v[66:67], v[58:59], v[66:67]
	v_pk_add_f32 v[74:75], v[56:57], v[74:75]
	v_cvt_pk_bf16_f32 v56, v72, v73
	v_cvt_pk_bf16_f32 v57, v64, v65
	v_mul_f32_e32 v73, v73, v73
	v_cvt_pk_bf16_f32 v58, v74, v75
	v_cvt_pk_bf16_f32 v59, v66, v67
	s_nop 1
	s_waitcnt vmcnt(14)
	v_mul_f32_e32 v65, v65, v65
	v_mul_f32_e32 v75, v75, v75
	v_fmac_f32_e32 v73, v72, v72
	v_fmac_f32_e32 v65, v64, v64
	v_mul_f32_e32 v67, v67, v67
	v_fmac_f32_e32 v75, v74, v74
	v_add_f32_e32 v64, v73, v65
	v_fmac_f32_e32 v67, v66, v66
	v_add_f32_e32 v64, v75, v64
	v_add_f32_e32 v72, v67, v64
	global_store_dwordx4 v[68:69], v[56:59], off
	s_nop 0
	v_lshlrev_b32_e32 v64, 16, v198
	v_and_b32_e32 v65, 0xffff0000, v198
	v_lshlrev_b32_e32 v60, 16, v199
	v_and_b32_e32 v61, 0xffff0000, v199
	v_lshlrev_b32_e32 v66, 16, v200
	v_and_b32_e32 v67, 0xffff0000, v200
	v_lshlrev_b32_e32 v62, 16, v201
	v_and_b32_e32 v63, 0xffff0000, v201
	v_pk_add_f32 v[54:55], v[54:55], v[60:61]
	v_pk_add_f32 v[52:53], v[52:53], v[64:65]
	v_pk_add_f32 v[60:61], v[50:51], v[62:63]
	v_pk_add_f32 v[62:63], v[48:49], v[66:67]
	v_mul_f32_e32 v48, v53, v53
	v_mul_f32_e32 v49, v55, v55
	v_mul_f32_e32 v50, v63, v63
	v_fmac_f32_e32 v48, v52, v52
	v_fmac_f32_e32 v49, v54, v54
	v_mul_f32_e32 v51, v61, v61
	v_fmac_f32_e32 v50, v62, v62
	v_add_f32_e32 v48, v48, v49
	v_add_f32_e32 v48, v50, v48
	v_fmac_f32_e32 v51, v60, v60
	v_add_f32_e32 v48, v51, v48
	v_add_f32_e32 v48, v72, v48
	ds_bpermute_b32 v49, v114, v48
	v_cvt_pk_bf16_f32 v50, v52, v53
	v_cvt_pk_bf16_f32 v51, v54, v55
	v_cvt_pk_bf16_f32 v52, v62, v63
	v_cvt_pk_bf16_f32 v53, v60, v61
	s_waitcnt lgkmcnt(0)
	v_add_f32_e32 v48, v48, v49
	ds_bpermute_b32 v49, v115, v48
	global_store_dwordx4 v[70:71], v[50:53], off offset:64
	s_and_saveexec_b64 s[24:25], s[2:3]
	s_cbranch_execz .LBB0_808
	s_waitcnt lgkmcnt(0)
	v_add_f32_e32 v48, v48, v49
	global_atomic_add_f32 v[112:113], v48, off offset:512
; __device__ __forceinline__ u32x4 pack8(f32x4 a, f32x4 b) { u32x4 w; w.x = cvt_pk_bf16(a[0], a[1]); w.y = cvt_pk_bf16(a[2], a[3]); w.z = cvt_pk_bf16(b[0], b[1]); w.w = cvt_pk_bf16(b[2], b[3]); return w; }
;     __device__ __forceinline__ void operator()(const f32x4 (&acc)[2][2][4][2], const Unit& u, int wr, int wc, int fr, int fq) const {
;     ...
;         for (int ai = 0; ai < 2; ++ai)
; #pragma unroll
;             for (int m = 0; m < 4; ++m) {
;                 const int row = row0 + ai * HALF + m * 16; const size_t off = (size_t)row * 2048 + col;
;                 float s = 0.f;
; #pragma unroll
;                 for (int bj = 0; bj < 2; ++bj) {
;                     f32x4 b0, b1;
;                     if (BASE_F32) { const float* bp = (const float*)base + off + bj * 32; b0 = *(const f32x4*)bp; b1 = *(const f32x4*)(bp + 4); }
;                     else { const u32x4 w = *(const u32x4*)((const bf16_t*)base + off + bj * 32);
;                         b0 = (f32x4){__uint_as_float(w.x << 16), __uint_as_float(w.x & 0xffff0000u), __uint_as_float(w.y << 16), __uint_as_float(w.y & 0xffff0000u)};
;                         b1 = (f32x4){__uint_as_float(w.z << 16), __uint_as_float(w.z & 0xffff0000u), __uint_as_float(w.w << 16), __uint_as_float(w.w & 0xffff0000u)}; }
;                     const f32x4 h0 = b0 + acc[ai][bj][m][0], h1 = b1 + acc[ai][bj][m][1];
;                     s += (h0[0] * h0[0] + h0[1] * h0[1]) + (h0[2] * h0[2] + h0[3] * h0[3]) + (h1[0] * h1[0] + h1[1] * h1[1]) + (h1[2] * h1[2] + h1[3] * h1[3]);
;                     *(u32x4*)(H + off + bj * 32) = pack8(h0, h1);
;                 }
;                 s += __shfl_xor(s, 16); s += __shfl_xor(s, 32);
;                 if (fq == 0) __hip_atomic_fetch_add(ss + row, s, __ATOMIC_RELAXED, __HIP_MEMORY_SCOPE_AGENT);
;                 if (m & 1) asm volatile("" ::: "memory");
;             }
.LBB0_808:
	s_or_b64 exec, exec, s[24:25]
	v_add_co_u32_e32 v52, vcc, 0x90000, v134
	s_mov_b64 s[24:25], 0x90000
	s_nop 0
	v_addc_co_u32_e32 v53, vcc, 0, v135, vcc
	s_waitcnt lgkmcnt(0)
	s_nop 1
	s_waitcnt vmcnt(15)
	v_lshl_add_u64 v[54:55], v[134:135], 0, s[24:25]
	s_nop 0
	v_lshlrev_b32_e32 v56, 16, v212
	v_and_b32_e32 v57, 0xffff0000, v212
	v_lshlrev_b32_e32 v48, 16, v213
	v_and_b32_e32 v49, 0xffff0000, v213
	v_lshlrev_b32_e32 v58, 16, v214
	v_and_b32_e32 v59, 0xffff0000, v214
	v_lshlrev_b32_e32 v50, 16, v215
	v_and_b32_e32 v51, 0xffff0000, v215
	v_pk_add_f32 v[48:49], v[46:47], v[48:49]
	v_pk_add_f32 v[56:57], v[44:45], v[56:57]
	v_pk_add_f32 v[50:51], v[42:43], v[50:51]
	v_pk_add_f32 v[58:59], v[40:41], v[58:59]
	v_cvt_pk_bf16_f32 v40, v56, v57
	v_cvt_pk_bf16_f32 v41, v48, v49
	v_mul_f32_e32 v57, v57, v57
	v_cvt_pk_bf16_f32 v42, v58, v59
	v_cvt_pk_bf16_f32 v43, v50, v51
	s_nop 1
	s_waitcnt vmcnt(14)
	v_mul_f32_e32 v49, v49, v49
	v_mul_f32_e32 v59, v59, v59
	v_fmac_f32_e32 v57, v56, v56
	v_fmac_f32_e32 v49, v48, v48
	v_mul_f32_e32 v51, v51, v51
	v_fmac_f32_e32 v59, v58, v58
	v_add_f32_e32 v48, v57, v49
	v_fmac_f32_e32 v51, v50, v50
	v_add_f32_e32 v48, v59, v48
	v_add_f32_e32 v56, v51, v48
	global_store_dwordx4 v[52:53], v[40:43], off
	s_nop 0
	v_lshlrev_b32_e32 v48, 16, v216
	v_and_b32_e32 v49, 0xffff0000, v216
	v_lshlrev_b32_e32 v44, 16, v217
	v_and_b32_e32 v45, 0xffff0000, v217
	v_lshlrev_b32_e32 v50, 16, v218
	v_and_b32_e32 v51, 0xffff0000, v218
	v_lshlrev_b32_e32 v46, 16, v219
	v_and_b32_e32 v47, 0xffff0000, v219
	v_pk_add_f32 v[38:39], v[38:39], v[44:45]
	v_pk_add_f32 v[36:37], v[36:37], v[48:49]
	v_pk_add_f32 v[44:45], v[34:35], v[46:47]
	v_pk_add_f32 v[46:47], v[32:33], v[50:51]
	v_mul_f32_e32 v32, v37, v37
	v_mul_f32_e32 v33, v39, v39
	v_mul_f32_e32 v34, v47, v47
	v_fmac_f32_e32 v32, v36, v36
	v_fmac_f32_e32 v33, v38, v38
	v_mul_f32_e32 v35, v45, v45
	v_fmac_f32_e32 v34, v46, v46
	v_add_f32_e32 v32, v32, v33
	v_add_f32_e32 v32, v34, v32
	v_fmac_f32_e32 v35, v44, v44
	v_add_f32_e32 v32, v35, v32
	v_add_f32_e32 v32, v56, v32
	ds_bpermute_b32 v33, v114, v32
	v_cvt_pk_bf16_f32 v34, v36, v37
	v_cvt_pk_bf16_f32 v35, v38, v39
	v_cvt_pk_bf16_f32 v36, v46, v47
	v_cvt_pk_bf16_f32 v37, v44, v45
	s_waitcnt lgkmcnt(0)
	v_add_f32_e32 v32, v32, v33
	ds_bpermute_b32 v33, v115, v32
	global_store_dwordx4 v[54:55], v[34:37], off offset:64
	s_and_saveexec_b64 s[24:25], s[2:3]
	s_cbranch_execz .LBB0_810
	s_waitcnt lgkmcnt(0)
	v_add_f32_e32 v32, v32, v33
	global_atomic_add_f32 v[112:113], v32, off offset:576
; __device__ __forceinline__ u32x4 pack8(f32x4 a, f32x4 b) { u32x4 w; w.x = cvt_pk_bf16(a[0], a[1]); w.y = cvt_pk_bf16(a[2], a[3]); w.z = cvt_pk_bf16(b[0], b[1]); w.w = cvt_pk_bf16(b[2], b[3]); return w; }
;     __device__ __forceinline__ void operator()(const f32x4 (&acc)[2][2][4][2], const Unit& u, int wr, int wc, int fr, int fq) const {
;     ...
;         for (int ai = 0; ai < 2; ++ai)
; #pragma unroll
;             for (int m = 0; m < 4; ++m) {
;                 const int row = row0 + ai * HALF + m * 16; const size_t off = (size_t)row * 2048 + col;
;                 float s = 0.f;
; #pragma unroll
;                 for (int bj = 0; bj < 2; ++bj) {
;                     f32x4 b0, b1;
;                     if (BASE_F32) { const float* bp = (const float*)base + off + bj * 32; b0 = *(const f32x4*)bp; b1 = *(const f32x4*)(bp + 4); }
;                     else { const u32x4 w = *(const u32x4*)((const bf16_t*)base + off + bj * 32);
;                         b0 = (f32x4){__uint_as_float(w.x << 16), __uint_as_float(w.x & 0xffff0000u), __uint_as_float(w.y << 16), __uint_as_float(w.y & 0xffff0000u)};
;                         b1 = (f32x4){__uint_as_float(w.z << 16), __uint_as_float(w.z & 0xffff0000u), __uint_as_float(w.w << 16), __uint_as_float(w.w & 0xffff0000u)}; }
;                     const f32x4 h0 = b0 + acc[ai][bj][m][0], h1 = b1 + acc[ai][bj][m][1];
;                     s += (h0[0] * h0[0] + h0[1] * h0[1]) + (h0[2] * h0[2] + h0[3] * h0[3]) + (h1[0] * h1[0] + h1[1] * h1[1]) + (h1[2] * h1[2] + h1[3] * h1[3]);
;                     *(u32x4*)(H + off + bj * 32) = pack8(h0, h1);
;                 }
;                 s += __shfl_xor(s, 16); s += __shfl_xor(s, 32);
;                 if (fq == 0) __hip_atomic_fetch_add(ss + row, s, __ATOMIC_RELAXED, __HIP_MEMORY_SCOPE_AGENT);
;                 if (m & 1) asm volatile("" ::: "memory");
;             }
.LBB0_810:
	s_or_b64 exec, exec, s[24:25]
	v_add_co_u32_e32 v36, vcc, 0xa0000, v134
	s_mov_b64 s[24:25], 0xa0000
	s_nop 0
	v_addc_co_u32_e32 v37, vcc, 0, v135, vcc
	s_waitcnt lgkmcnt(0)
	s_nop 1
	s_waitcnt vmcnt(14)
	v_lshl_add_u64 v[38:39], v[134:135], 0, s[24:25]
	s_nop 0
	v_lshlrev_b32_e32 v40, 16, v154
	v_and_b32_e32 v41, 0xffff0000, v154
	v_lshlrev_b32_e32 v32, 16, v155
	v_and_b32_e32 v33, 0xffff0000, v155
	v_lshlrev_b32_e32 v42, 16, v156
	v_and_b32_e32 v43, 0xffff0000, v156
	v_lshlrev_b32_e32 v34, 16, v157
	v_and_b32_e32 v35, 0xffff0000, v157
	v_pk_add_f32 v[32:33], v[30:31], v[32:33]
	v_pk_add_f32 v[40:41], v[28:29], v[40:41]
	v_pk_add_f32 v[34:35], v[26:27], v[34:35]
	v_pk_add_f32 v[42:43], v[24:25], v[42:43]
	v_cvt_pk_bf16_f32 v24, v40, v41
	v_cvt_pk_bf16_f32 v25, v32, v33
	v_mul_f32_e32 v41, v41, v41
	v_cvt_pk_bf16_f32 v26, v42, v43
	v_cvt_pk_bf16_f32 v27, v34, v35
	s_nop 1
	s_waitcnt vmcnt(13)
	v_mul_f32_e32 v33, v33, v33
	v_mul_f32_e32 v43, v43, v43
	v_fmac_f32_e32 v41, v40, v40
	v_fmac_f32_e32 v33, v32, v32
	v_mul_f32_e32 v35, v35, v35
	v_fmac_f32_e32 v43, v42, v42
	v_add_f32_e32 v32, v41, v33
	v_fmac_f32_e32 v35, v34, v34
	v_add_f32_e32 v32, v43, v32
	v_add_f32_e32 v40, v35, v32
	global_store_dwordx4 v[36:37], v[24:27], off
	s_nop 0
	v_lshlrev_b32_e32 v32, 16, v158
	v_and_b32_e32 v33, 0xffff0000, v158
	v_lshlrev_b32_e32 v28, 16, v159
	v_and_b32_e32 v29, 0xffff0000, v159
	v_lshlrev_b32_e32 v34, 16, v160
	v_and_b32_e32 v35, 0xffff0000, v160
	v_lshlrev_b32_e32 v30, 16, v161
	v_and_b32_e32 v31, 0xffff0000, v161
	v_pk_add_f32 v[22:23], v[22:23], v[28:29]
	v_pk_add_f32 v[20:21], v[20:21], v[32:33]
	v_pk_add_f32 v[28:29], v[18:19], v[30:31]
	v_pk_add_f32 v[30:31], v[16:17], v[34:35]
	v_mul_f32_e32 v16, v21, v21
	v_mul_f32_e32 v17, v23, v23
	v_mul_f32_e32 v18, v31, v31
	v_fmac_f32_e32 v16, v20, v20
	v_fmac_f32_e32 v17, v22, v22
	v_mul_f32_e32 v19, v29, v29
	v_fmac_f32_e32 v18, v30, v30
	v_add_f32_e32 v16, v16, v17
	v_add_f32_e32 v16, v18, v16
	v_fmac_f32_e32 v19, v28, v28
	v_add_f32_e32 v16, v19, v16
	v_add_f32_e32 v16, v40, v16
	ds_bpermute_b32 v17, v114, v16
	v_cvt_pk_bf16_f32 v18, v20, v21
	v_cvt_pk_bf16_f32 v19, v22, v23
	v_cvt_pk_bf16_f32 v20, v30, v31
	v_cvt_pk_bf16_f32 v21, v28, v29
	s_waitcnt lgkmcnt(0)
	v_add_f32_e32 v16, v16, v17
	ds_bpermute_b32 v17, v115, v16
	global_store_dwordx4 v[38:39], v[18:21], off offset:64
	s_and_saveexec_b64 s[24:25], s[2:3]
	s_cbranch_execz .LBB0_812
	s_waitcnt lgkmcnt(0)
	v_add_f32_e32 v16, v16, v17
	global_atomic_add_f32 v[112:113], v16, off offset:640
.LBB0_812:
	s_or_b64 exec, exec, s[24:25]
	v_add_co_u32_e32 v20, vcc, 0xb0000, v134
	s_mov_b64 s[24:25], 0xb0000
	s_nop 0
	v_addc_co_u32_e32 v21, vcc, 0, v135, vcc
	s_waitcnt lgkmcnt(0)
	s_nop 1
	s_waitcnt vmcnt(12)
	v_lshl_add_u64 v[22:23], v[134:135], 0, s[24:25]
	s_nop 0
	v_lshlrev_b32_e32 v24, 16, v162
	v_and_b32_e32 v25, 0xffff0000, v162
	v_lshlrev_b32_e32 v16, 16, v163
	v_and_b32_e32 v17, 0xffff0000, v163
	v_lshlrev_b32_e32 v26, 16, v164
	v_and_b32_e32 v27, 0xffff0000, v164
	v_lshlrev_b32_e32 v18, 16, v165
	v_and_b32_e32 v19, 0xffff0000, v165
	v_pk_add_f32 v[16:17], v[14:15], v[16:17]
	v_pk_add_f32 v[24:25], v[12:13], v[24:25]
	v_pk_add_f32 v[18:19], v[10:11], v[18:19]
	v_pk_add_f32 v[26:27], v[8:9], v[26:27]
	v_cvt_pk_bf16_f32 v8, v24, v25
	v_cvt_pk_bf16_f32 v9, v16, v17
	v_mul_f32_e32 v25, v25, v25
	v_cvt_pk_bf16_f32 v10, v26, v27
	v_cvt_pk_bf16_f32 v11, v18, v19
	s_nop 1
	s_waitcnt vmcnt(11)
	v_mul_f32_e32 v17, v17, v17
	v_mul_f32_e32 v27, v27, v27
	v_fmac_f32_e32 v25, v24, v24
	v_fmac_f32_e32 v17, v16, v16
	v_mul_f32_e32 v19, v19, v19
	v_fmac_f32_e32 v27, v26, v26
	v_add_f32_e32 v16, v25, v17
	v_fmac_f32_e32 v19, v18, v18
	v_add_f32_e32 v16, v27, v16
	v_add_f32_e32 v24, v19, v16
	global_store_dwordx4 v[20:21], v[8:11], off
	s_nop 0
	v_lshlrev_b32_e32 v16, 16, v166
	v_and_b32_e32 v17, 0xffff0000, v166
	v_lshlrev_b32_e32 v12, 16, v167
	v_and_b32_e32 v13, 0xffff0000, v167
	v_lshlrev_b32_e32 v18, 16, v168
	v_and_b32_e32 v19, 0xffff0000, v168
	v_lshlrev_b32_e32 v14, 16, v169
	v_and_b32_e32 v15, 0xffff0000, v169
	v_pk_add_f32 v[6:7], v[6:7], v[12:13]
	v_pk_add_f32 v[4:5], v[4:5], v[16:17]
	v_pk_add_f32 v[12:13], v[2:3], v[14:15]
	v_pk_add_f32 v[14:15], v[0:1], v[18:19]
	v_mul_f32_e32 v0, v5, v5
	v_mul_f32_e32 v1, v7, v7
	v_mul_f32_e32 v2, v15, v15
	v_fmac_f32_e32 v0, v4, v4
	v_fmac_f32_e32 v1, v6, v6
	v_mul_f32_e32 v3, v13, v13
	v_fmac_f32_e32 v2, v14, v14
	v_add_f32_e32 v0, v0, v1
	v_add_f32_e32 v0, v2, v0
	v_fmac_f32_e32 v3, v12, v12
	v_add_f32_e32 v0, v3, v0
	v_add_f32_e32 v0, v24, v0
	ds_bpermute_b32 v1, v114, v0
	v_cvt_pk_bf16_f32 v2, v4, v5
	v_cvt_pk_bf16_f32 v3, v6, v7
	v_cvt_pk_bf16_f32 v4, v14, v15
	v_cvt_pk_bf16_f32 v5, v12, v13
	s_waitcnt lgkmcnt(0)
	v_add_f32_e32 v0, v0, v1
	ds_bpermute_b32 v1, v115, v0
	global_store_dwordx4 v[22:23], v[2:5], off offset:64
	s_and_saveexec_b64 s[24:25], s[2:3]
	s_cbranch_execz .LBB0_814
	s_waitcnt lgkmcnt(0)
	v_add_f32_e32 v0, v0, v1
	global_atomic_add_f32 v[112:113], v0, off offset:704
